# per-segment s_setprio flips deleted, one static priority raise for waves 0-3 (probe: -1.3 us per GEMM phase vs the flips)
# speedup vs baseline: 1.0119x; 1.0074x over previous
; #define LAS __attribute__((address_space(3)))
; __device__ __forceinline__ unsigned xb_add(unsigned* p, unsigned v) { return __hip_atomic_fetch_add(p, v, __ATOMIC_RELAXED, __HIP_MEMORY_SCOPE_AGENT); }
; __device__ __forceinline__ unsigned xb_xcc_id() { return (unsigned)__builtin_amdgcn_s_getreg((3 << 11) | 20) & 0xFu; }
; __device__ __forceinline__ XcdBarrier xcd_barrier_post(unsigned* bar, volatile LAS unsigned* st) {
;     XcdBarrier b; b.bar = bar; b.x = xb_xcc_id(); b.st = st;
;     if (threadIdx.x == 0) (void)xb_add(&bar[XB_XCNT(b.x)], 1u);
;     return b;
; __global__ void __launch_bounds__(NTHREADS) mega(Args args) {
;     ...
;     F.lds = (LAS unsigned char*)lds_raw;
;     F.tid = threadIdx.x; F.lane = F.tid & 63; F.wave = __builtin_amdgcn_readfirstlane(F.tid >> 6);
;     F.G = gridDim.x; F.bid = blockIdx.x;
;     volatile LAS unsigned* bst = (volatile LAS unsigned*)(F.lds + LDS_WORK);
;     if (F.tid < 4) bst[F.tid] = 0u;
;     __syncthreads();
;     XcdBarrier xbar = xcd_barrier_post((unsigned*)(args.ws + WS_BAR), bst);
_Z4mega4Args:
	s_mov_b32 s32, 0
	v_readfirstlane_b32 s98, v0
	s_nop 3
	s_and_b32 s98, s98, 0x3ff
	s_lshr_b32 s98, s98, 6
	s_cmp_ge_u32 s98, 4
	s_cbranch_scc1 .Lprio_done
	s_setprio 1
.Lprio_done:
	s_mov_b32 s44, s2
	s_add_u32 s2, s0, 0xd0
	s_addc_u32 s3, s1, 0
	v_and_b32_e32 v138, 0x3ff, v0
	v_writelane_b32 v254, s2, 0
	v_readfirstlane_b32 s6, v138
	v_cmp_gt_u32_e32 vcc, 4, v138
	v_writelane_b32 v254, s3, 1
	s_and_saveexec_b64 s[2:3], vcc
	v_lshl_add_u32 v1, v138, 2, 0
	v_add_u32_e32 v1, 0x20000, v1
	v_mov_b32_e32 v2, 0
	ds_write_b32 v1, v2
	s_or_b64 exec, exec, s[2:3]
	s_waitcnt lgkmcnt(0)
	s_barrier
	s_getreg_b32 s2, hwreg(HW_REG_XCC_ID, 0, 4)
	s_and_b32 s2, s2, 15
	v_writelane_b32 v254, s2, 2
	v_cmp_eq_u32_e64 s[4:5], 0, v138
	s_mov_b64 s[2:3], exec
	s_nop 0
	v_writelane_b32 v254, s4, 3
	s_nop 1
	v_writelane_b32 v254, s5, 4
	s_and_b64 s[4:5], s[2:3], s[4:5]
	s_mov_b64 exec, s[4:5]
	s_cbranch_execz .LBB0_5
	s_mov_b64 s[4:5], exec
	v_mbcnt_lo_u32_b32 v1, s4, 0
	v_mbcnt_hi_u32_b32 v1, s5, v1
	v_cmp_eq_u32_e32 vcc, 0, v1
	s_and_b64 s[8:9], exec, vcc
	s_mov_b64 exec, s[8:9]
	s_cbranch_execz .LBB0_5
	s_bcnt1_i32_b64 s4, s[4:5]
	v_mov_b32_e32 v2, s4
	s_load_dwordx2 s[4:5], s[0:1], 0xb8
	v_readlane_b32 s7, v254, 2
	s_lshl_b32 s7, s7, 8
	s_nop 0
	v_mov_b32_e32 v1, s7
	s_waitcnt lgkmcnt(0)
	global_atomic_add v1, v2, s[4:5] offset:1024

; #define PG8_STAGE(bufoff, gbase, voff) do { _Pragma("unroll") for (int _i = 0; _i < 2; ++_i) \
;         __builtin_amdgcn_global_load_lds((const unsigned*)((const char*)(gbase) + (voff)[_i]), (LAS unsigned*)(lds + (bufoff) + ldsw + _i * 8192), 16, 0, 0); } while (0)
; #define PG8_LDA(dst, b, h) do { _Pragma("unroll") for (int m = 0; m < 4; ++m) _Pragma("unroll") for (int k = 0; k < 2; ++k) dst[m][k] = *(const LAS bf16x8*)(lds + PG8_SA(b, h) + aoff + m * 2048 + k * 1024); } while (0)
; #define PG8_LDB(dst, b, h) do { _Pragma("unroll") for (int n = 0; n < 2; ++n) _Pragma("unroll") for (int k = 0; k < 2; ++k) dst[n][k] = *(const LAS bf16x8*)(lds + PG8_SB(b, h) + boff + n * 2048 + k * 1024); } while (0)
; #define PG8_MMA(ai, bj, At, Bt) do { __builtin_amdgcn_s_setprio(1); _Pragma("unroll") for (int m = 0; m < 4; ++m) _Pragma("unroll") for (int n = 0; n < 2; ++n) _Pragma("unroll") for (int k = 0; k < 2; ++k) \
;         acc[ai][bj][m][n] = __builtin_amdgcn_mfma_f32_16x16x32_bf16(Bt[n][k], At[m][k], acc[ai][bj][m][n], 0, 0, 0); __builtin_amdgcn_s_setprio(0); } while (0)
; #define PG8_WAIT_V(n) asm volatile("s_waitcnt vmcnt(" #n ")" ::: "memory")
; #define PG8_WAIT_L(n) asm volatile("s_waitcnt lgkmcnt(" #n ")" ::: "memory")
; template <class Epi>
; __device__ __forceinline__ void gemm_phase(LAS unsigned char* lds, const Gemm g, const Epi& E) {
;     ...
;             PG8_LDB(B0, 0, 0); PG8_LDB(B1, 0, 1); PG8_SCHED; PG8_LDA(At, 0, 0); PG8_STAGE(PG8_SA(1, 1), a1 + hstep, voffA);
;             PG8_WAIT_V(8); PG8_WAIT_L(0); PG8_BAR; PG8_MMA(0, 0, At, B0); PG8_MMA(0, 1, At, B1); PG8_BAR; PG8_SCHED;
;             PG8_LDA(At, 0, 1); PG8_STAGE(PG8_SB(0, 0), b2, voffA); PG8_STAGE(PG8_SB(0, 1), b2 + hstep, voffA); PG8_STAGE(PG8_SA(0, 0), a2, voffA);
;             PG8_WAIT_V(8); PG8_WAIT_L(0); PG8_BAR; PG8_MMA(1, 0, At, B0); PG8_MMA(1, 1, At, B1); PG8_BAR; PG8_SCHED;
;             PG8_LDB(B0, 1, 0); PG8_LDB(B1, 1, 1); PG8_SCHED; PG8_LDA(At, 1, 0); PG8_STAGE(PG8_SA(0, 1), a2 + hstep, voffA);
;             PG8_WAIT_V(8); PG8_WAIT_L(0); PG8_BAR; PG8_MMA(0, 0, At, B0); PG8_MMA(0, 1, At, B1); PG8_BAR; PG8_SCHED;
;             PG8_LDA(At, 1, 1); PG8_STAGE(PG8_SB(1, 0), b3, voffA); PG8_STAGE(PG8_SB(1, 1), b3 + hstep, voffA); PG8_STAGE(PG8_SA(1, 0), a3, voffA);
;             PG8_WAIT_V(8); PG8_WAIT_L(0); PG8_BAR; PG8_MMA(1, 0, At, B0); PG8_MMA(1, 1, At, B1); PG8_BAR; PG8_SCHED;
.Lrw1a_d:
	s_waitcnt lgkmcnt(0)
	s_barrier
	s_waitcnt lgkmcnt(0)
	v_mfma_f32_16x16x32_bf16 v[122:125], v[130:133], v[202:205], v[122:125]
	v_mfma_f32_16x16x32_bf16 v[126:129], v[152:155], v[202:205], v[126:129]
	v_mfma_f32_16x16x32_bf16 v[106:109], v[130:133], v[210:213], v[106:109]
	v_mfma_f32_16x16x32_bf16 v[110:113], v[152:155], v[210:213], v[110:113]
	v_mfma_f32_16x16x32_bf16 v[90:93], v[130:133], v[218:221], v[90:93]
	v_mfma_f32_16x16x32_bf16 v[94:97], v[152:155], v[218:221], v[94:97]
	v_mfma_f32_16x16x32_bf16 v[74:77], v[130:133], v[226:229], v[74:77]
	v_mfma_f32_16x16x32_bf16 v[78:81], v[152:155], v[226:229], v[78:81]
	v_mfma_f32_16x16x32_bf16 v[122:125], v[134:137], v[206:209], v[122:125]
	v_mfma_f32_16x16x32_bf16 v[126:129], v[156:159], v[206:209], v[126:129]
	v_mfma_f32_16x16x32_bf16 v[106:109], v[134:137], v[214:217], v[106:109]
	v_mfma_f32_16x16x32_bf16 v[110:113], v[156:159], v[214:217], v[110:113]
	v_mfma_f32_16x16x32_bf16 v[90:93], v[134:137], v[222:225], v[90:93]
	v_mfma_f32_16x16x32_bf16 v[94:97], v[156:159], v[222:225], v[94:97]
	v_mfma_f32_16x16x32_bf16 v[74:77], v[134:137], v[230:233], v[74:77]
	v_mfma_f32_16x16x32_bf16 v[78:81], v[156:159], v[230:233], v[78:81]
	v_mfma_f32_16x16x32_bf16 v[114:117], v[160:163], v[202:205], v[114:117]
	v_mfma_f32_16x16x32_bf16 v[118:121], v[194:197], v[202:205], v[118:121]
	v_mfma_f32_16x16x32_bf16 v[98:101], v[160:163], v[210:213], v[98:101]
	v_mfma_f32_16x16x32_bf16 v[102:105], v[194:197], v[210:213], v[102:105]
	v_mfma_f32_16x16x32_bf16 v[82:85], v[160:163], v[218:221], v[82:85]
	v_mfma_f32_16x16x32_bf16 v[86:89], v[194:197], v[218:221], v[86:89]
	v_mfma_f32_16x16x32_bf16 v[66:69], v[160:163], v[226:229], v[66:69]
	v_mfma_f32_16x16x32_bf16 v[70:73], v[194:197], v[226:229], v[70:73]
	v_mfma_f32_16x16x32_bf16 v[114:117], v[190:193], v[206:209], v[114:117]
	v_mfma_f32_16x16x32_bf16 v[118:121], v[198:201], v[206:209], v[118:121]
	v_mfma_f32_16x16x32_bf16 v[98:101], v[190:193], v[214:217], v[98:101]
	v_mfma_f32_16x16x32_bf16 v[102:105], v[198:201], v[214:217], v[102:105]
	v_mfma_f32_16x16x32_bf16 v[82:85], v[190:193], v[222:225], v[82:85]
	v_mfma_f32_16x16x32_bf16 v[86:89], v[198:201], v[222:225], v[86:89]
	v_mfma_f32_16x16x32_bf16 v[66:69], v[190:193], v[230:233], v[66:69]
	v_mfma_f32_16x16x32_bf16 v[70:73], v[198:201], v[230:233], v[70:73]
	s_barrier
	s_add_i32 s79, s21, s26
	v_lshl_add_u64 v[164:165], s[4:5], 0, v[0:1]
	s_mov_b32 m0, s79
	ds_read_b128 v[202:205], v167 offset:16384
	ds_read_b128 v[206:209], v167 offset:17408
	ds_read_b128 v[210:213], v167 offset:18432
	ds_read_b128 v[214:217], v167 offset:19456
	ds_read_b128 v[218:221], v167 offset:20480
	ds_read_b128 v[222:225], v167 offset:21504
	ds_read_b128 v[226:229], v167 offset:22528
	ds_read_b128 v[230:233], v167 offset:23552
	global_load_lds_dwordx4 v[164:165], off
	s_add_i32 m0, s79, 0x2000
	s_add_u32 vcc_lo, s4, 0x40000
	v_lshl_add_u64 v[168:169], s[4:5], 0, v[146:147]
	s_addc_u32 vcc_hi, s5, 0
	s_add_i32 s25, s25, s26
	global_load_lds_dwordx4 v[168:169], off
	v_lshl_add_u64 v[234:235], vcc, 0, v[0:1]
	s_mov_b32 m0, s25
	v_lshl_add_u64 v[236:237], s[10:11], 0, v[146:147]
	global_load_lds_dwordx4 v[234:235], off
	v_lshl_add_u64 v[234:235], vcc, 0, v[146:147]
	s_add_i32 m0, s25, 0x2000
	s_nop 0
	global_load_lds_dwordx4 v[234:235], off
	v_lshl_add_u64 v[234:235], s[10:11], 0, v[0:1]
	s_mov_b32 m0, s53
	s_nop 0
	global_load_lds_dwordx4 v[234:235], off
	s_mov_b32 m0, s73
	s_nop 0
	global_load_lds_dwordx4 v[236:237], off
	s_cmp_eq_u32 s32, 1
	s_cbranch_scc1 .Lrw1b_1
	s_cmp_eq_u32 s32, 2
	s_cbranch_scc1 .Lrw1b_2
	s_waitcnt vmcnt(63)
	s_branch .Lrw1b_d

; #define PG8_STAGE(bufoff, gbase, voff) do { _Pragma("unroll") for (int _i = 0; _i < 2; ++_i) \
;         __builtin_amdgcn_global_load_lds((const unsigned*)((const char*)(gbase) + (voff)[_i]), (LAS unsigned*)(lds + (bufoff) + ldsw + _i * 8192), 16, 0, 0); } while (0)
; #define PG8_LDA(dst, b, h) do { _Pragma("unroll") for (int m = 0; m < 4; ++m) _Pragma("unroll") for (int k = 0; k < 2; ++k) dst[m][k] = *(const LAS bf16x8*)(lds + PG8_SA(b, h) + aoff + m * 2048 + k * 1024); } while (0)
; #define PG8_LDB(dst, b, h) do { _Pragma("unroll") for (int n = 0; n < 2; ++n) _Pragma("unroll") for (int k = 0; k < 2; ++k) dst[n][k] = *(const LAS bf16x8*)(lds + PG8_SB(b, h) + boff + n * 2048 + k * 1024); } while (0)
; #define PG8_MMA(ai, bj, At, Bt) do { __builtin_amdgcn_s_setprio(1); _Pragma("unroll") for (int m = 0; m < 4; ++m) _Pragma("unroll") for (int n = 0; n < 2; ++n) _Pragma("unroll") for (int k = 0; k < 2; ++k) \
;         acc[ai][bj][m][n] = __builtin_amdgcn_mfma_f32_16x16x32_bf16(Bt[n][k], At[m][k], acc[ai][bj][m][n], 0, 0, 0); __builtin_amdgcn_s_setprio(0); } while (0)
; #define PG8_WAIT_V(n) asm volatile("s_waitcnt vmcnt(" #n ")" ::: "memory")
; #define PG8_WAIT_L(n) asm volatile("s_waitcnt lgkmcnt(" #n ")" ::: "memory")
; template <class Epi>
; __device__ __forceinline__ void gemm_phase(LAS unsigned char* lds, const Gemm g, const Epi& E) {
;     ...
;             PG8_LDB(B0, 0, 0); PG8_LDB(B1, 0, 1); PG8_SCHED; PG8_LDA(At, 0, 0); PG8_STAGE(PG8_SA(1, 1), a1 + hstep, voffA);
;             PG8_WAIT_V(8); PG8_WAIT_L(0); PG8_BAR; PG8_MMA(0, 0, At, B0); PG8_MMA(0, 1, At, B1); PG8_BAR; PG8_SCHED;
;             PG8_LDA(At, 0, 1); PG8_STAGE(PG8_SB(0, 0), b2, voffA); PG8_STAGE(PG8_SB(0, 1), b2 + hstep, voffA); PG8_STAGE(PG8_SA(0, 0), a2, voffA);
;             PG8_WAIT_V(8); PG8_WAIT_L(0); PG8_BAR; PG8_MMA(1, 0, At, B0); PG8_MMA(1, 1, At, B1); PG8_BAR; PG8_SCHED;
;             PG8_LDB(B0, 1, 0); PG8_LDB(B1, 1, 1); PG8_SCHED; PG8_LDA(At, 1, 0); PG8_STAGE(PG8_SA(0, 1), a2 + hstep, voffA);
;             PG8_WAIT_V(8); PG8_WAIT_L(0); PG8_BAR; PG8_MMA(0, 0, At, B0); PG8_MMA(0, 1, At, B1); PG8_BAR; PG8_SCHED;
;             PG8_LDA(At, 1, 1); PG8_STAGE(PG8_SB(1, 0), b3, voffA); PG8_STAGE(PG8_SB(1, 1), b3 + hstep, voffA); PG8_STAGE(PG8_SA(1, 0), a3, voffA);
;             PG8_WAIT_V(8); PG8_WAIT_L(0); PG8_BAR; PG8_MMA(1, 0, At, B0); PG8_MMA(1, 1, At, B1); PG8_BAR; PG8_SCHED;
.Lrw1b_d:
	s_mov_b32 s32, 0
	s_waitcnt lgkmcnt(0)
	s_barrier
	s_waitcnt lgkmcnt(0)
	v_mfma_f32_16x16x32_bf16 v[58:61], v[130:133], v[202:205], v[58:61]
	v_mfma_f32_16x16x32_bf16 v[62:65], v[152:155], v[202:205], v[62:65]
	v_mfma_f32_16x16x32_bf16 v[42:45], v[130:133], v[210:213], v[42:45]
	v_mfma_f32_16x16x32_bf16 v[46:49], v[152:155], v[210:213], v[46:49]
	v_mfma_f32_16x16x32_bf16 v[26:29], v[130:133], v[218:221], v[26:29]
	v_mfma_f32_16x16x32_bf16 v[30:33], v[152:155], v[218:221], v[30:33]
	v_mfma_f32_16x16x32_bf16 v[10:13], v[130:133], v[226:229], v[10:13]
	v_mfma_f32_16x16x32_bf16 v[14:17], v[152:155], v[226:229], v[14:17]
	v_mfma_f32_16x16x32_bf16 v[58:61], v[134:137], v[206:209], v[58:61]
	v_mfma_f32_16x16x32_bf16 v[62:65], v[156:159], v[206:209], v[62:65]
	v_mfma_f32_16x16x32_bf16 v[42:45], v[134:137], v[214:217], v[42:45]
	v_mfma_f32_16x16x32_bf16 v[46:49], v[156:159], v[214:217], v[46:49]
	v_mfma_f32_16x16x32_bf16 v[26:29], v[134:137], v[222:225], v[26:29]
	v_mfma_f32_16x16x32_bf16 v[30:33], v[156:159], v[222:225], v[30:33]
	v_mfma_f32_16x16x32_bf16 v[10:13], v[134:137], v[230:233], v[10:13]
	v_mfma_f32_16x16x32_bf16 v[14:17], v[156:159], v[230:233], v[14:17]
	v_mfma_f32_16x16x32_bf16 v[50:53], v[160:163], v[202:205], v[50:53]
	v_mfma_f32_16x16x32_bf16 v[54:57], v[194:197], v[202:205], v[54:57]
	v_mfma_f32_16x16x32_bf16 v[34:37], v[160:163], v[210:213], v[34:37]
	v_mfma_f32_16x16x32_bf16 v[38:41], v[194:197], v[210:213], v[38:41]
	v_mfma_f32_16x16x32_bf16 v[18:21], v[160:163], v[218:221], v[18:21]
	v_mfma_f32_16x16x32_bf16 v[22:25], v[194:197], v[218:221], v[22:25]
	v_mfma_f32_16x16x32_bf16 v[6:9], v[160:163], v[226:229], v[6:9]
	v_mfma_f32_16x16x32_bf16 v[2:5], v[194:197], v[226:229], v[2:5]
	v_mfma_f32_16x16x32_bf16 v[50:53], v[190:193], v[206:209], v[50:53]
	v_mfma_f32_16x16x32_bf16 v[54:57], v[198:201], v[206:209], v[54:57]
	v_mfma_f32_16x16x32_bf16 v[34:37], v[190:193], v[214:217], v[34:37]
	v_mfma_f32_16x16x32_bf16 v[38:41], v[198:201], v[214:217], v[38:41]
	v_mfma_f32_16x16x32_bf16 v[18:21], v[190:193], v[222:225], v[18:21]
	v_mfma_f32_16x16x32_bf16 v[22:25], v[198:201], v[222:225], v[22:25]
	v_mfma_f32_16x16x32_bf16 v[6:9], v[190:193], v[230:233], v[6:9]
	v_mfma_f32_16x16x32_bf16 v[2:5], v[198:201], v[230:233], v[2:5]
	s_barrier
	s_add_i32 s25, 0, 0x18000
	s_add_i32 s79, 0, 0x1c000
	v_add_u32_e32 v156, s25, v166
	v_add_u32_e32 v189, s79, v166
	ds_read_b128 v[130:133], v156
	ds_read_b128 v[134:137], v156 offset:1024
	ds_read_b128 v[152:155], v156 offset:2048
	ds_read_b128 v[156:159], v156 offset:3072
	ds_read_b128 v[160:163], v189
	ds_read_b128 v[190:193], v189 offset:1024
	ds_read_b128 v[194:197], v189 offset:2048
	ds_read_b128 v[198:201], v189 offset:3072
	s_add_u32 s10, s10, 0x40000
	s_addc_u32 s11, s11, 0
	s_mov_b32 m0, s76
	v_lshl_add_u64 v[238:239], s[10:11], 0, v[0:1]
	ds_read_b128 v[202:205], v167 offset:32768
	ds_read_b128 v[206:209], v167 offset:33792
	ds_read_b128 v[210:213], v167 offset:34816
	ds_read_b128 v[214:217], v167 offset:35840
	ds_read_b128 v[218:221], v167 offset:36864
	ds_read_b128 v[222:225], v167 offset:37888
	ds_read_b128 v[226:229], v167 offset:38912
	ds_read_b128 v[230:233], v167 offset:39936
	global_load_lds_dwordx4 v[238:239], off
	v_lshl_add_u64 v[238:239], s[10:11], 0, v[146:147]
	s_mov_b32 m0, s77
	s_nop 0
	global_load_lds_dwordx4 v[238:239], off
	s_waitcnt vmcnt(8)
	s_waitcnt lgkmcnt(0)
	s_barrier
	s_waitcnt lgkmcnt(0)
	v_mfma_f32_16x16x32_bf16 v[122:125], v[130:133], v[202:205], v[122:125]
	v_mfma_f32_16x16x32_bf16 v[126:129], v[152:155], v[202:205], v[126:129]
	v_mfma_f32_16x16x32_bf16 v[106:109], v[130:133], v[210:213], v[106:109]
	v_mfma_f32_16x16x32_bf16 v[110:113], v[152:155], v[210:213], v[110:113]
	v_mfma_f32_16x16x32_bf16 v[90:93], v[130:133], v[218:221], v[90:93]
	v_mfma_f32_16x16x32_bf16 v[94:97], v[152:155], v[218:221], v[94:97]
	v_mfma_f32_16x16x32_bf16 v[74:77], v[130:133], v[226:229], v[74:77]
	v_mfma_f32_16x16x32_bf16 v[78:81], v[152:155], v[226:229], v[78:81]
	v_mfma_f32_16x16x32_bf16 v[122:125], v[134:137], v[206:209], v[122:125]
	v_mfma_f32_16x16x32_bf16 v[126:129], v[156:159], v[206:209], v[126:129]
	v_mfma_f32_16x16x32_bf16 v[106:109], v[134:137], v[214:217], v[106:109]
	v_mfma_f32_16x16x32_bf16 v[110:113], v[156:159], v[214:217], v[110:113]
	v_mfma_f32_16x16x32_bf16 v[90:93], v[134:137], v[222:225], v[90:93]
	v_mfma_f32_16x16x32_bf16 v[94:97], v[156:159], v[222:225], v[94:97]
	v_mfma_f32_16x16x32_bf16 v[74:77], v[134:137], v[230:233], v[74:77]
	v_mfma_f32_16x16x32_bf16 v[78:81], v[156:159], v[230:233], v[78:81]
	v_mfma_f32_16x16x32_bf16 v[114:117], v[160:163], v[202:205], v[114:117]
	v_mfma_f32_16x16x32_bf16 v[118:121], v[194:197], v[202:205], v[118:121]
	v_mfma_f32_16x16x32_bf16 v[98:101], v[160:163], v[210:213], v[98:101]
	v_mfma_f32_16x16x32_bf16 v[102:105], v[194:197], v[210:213], v[102:105]
	v_mfma_f32_16x16x32_bf16 v[82:85], v[160:163], v[218:221], v[82:85]
	v_mfma_f32_16x16x32_bf16 v[86:89], v[194:197], v[218:221], v[86:89]
	v_mfma_f32_16x16x32_bf16 v[66:69], v[160:163], v[226:229], v[66:69]
	v_mfma_f32_16x16x32_bf16 v[70:73], v[194:197], v[226:229], v[70:73]
	v_mfma_f32_16x16x32_bf16 v[114:117], v[190:193], v[206:209], v[114:117]
	v_mfma_f32_16x16x32_bf16 v[118:121], v[198:201], v[206:209], v[118:121]
	v_mfma_f32_16x16x32_bf16 v[98:101], v[190:193], v[214:217], v[98:101]
	v_mfma_f32_16x16x32_bf16 v[102:105], v[198:201], v[214:217], v[102:105]
	v_mfma_f32_16x16x32_bf16 v[82:85], v[190:193], v[222:225], v[82:85]
	v_mfma_f32_16x16x32_bf16 v[86:89], v[198:201], v[222:225], v[86:89]
	v_mfma_f32_16x16x32_bf16 v[66:69], v[190:193], v[230:233], v[66:69]
	v_mfma_f32_16x16x32_bf16 v[70:73], v[198:201], v[230:233], v[70:73]
	s_barrier
; #define PG8_STAGE(bufoff, gbase, voff) do { _Pragma("unroll") for (int _i = 0; _i < 2; ++_i) \
;         __builtin_amdgcn_global_load_lds((const unsigned*)((const char*)(gbase) + (voff)[_i]), (LAS unsigned*)(lds + (bufoff) + ldsw + _i * 8192), 16, 0, 0); } while (0)
; #define PG8_LDA(dst, b, h) do { _Pragma("unroll") for (int m = 0; m < 4; ++m) _Pragma("unroll") for (int k = 0; k < 2; ++k) dst[m][k] = *(const LAS bf16x8*)(lds + PG8_SA(b, h) + aoff + m * 2048 + k * 1024); } while (0)
; #define PG8_LDB(dst, b, h) do { _Pragma("unroll") for (int n = 0; n < 2; ++n) _Pragma("unroll") for (int k = 0; k < 2; ++k) dst[n][k] = *(const LAS bf16x8*)(lds + PG8_SB(b, h) + boff + n * 2048 + k * 1024); } while (0)
; #define PG8_MMA(ai, bj, At, Bt) do { __builtin_amdgcn_s_setprio(1); _Pragma("unroll") for (int m = 0; m < 4; ++m) _Pragma("unroll") for (int n = 0; n < 2; ++n) _Pragma("unroll") for (int k = 0; k < 2; ++k) \
;         acc[ai][bj][m][n] = __builtin_amdgcn_mfma_f32_16x16x32_bf16(Bt[n][k], At[m][k], acc[ai][bj][m][n], 0, 0, 0); __builtin_amdgcn_s_setprio(0); } while (0)
; #define PG8_WAIT_V(n) asm volatile("s_waitcnt vmcnt(" #n ")" ::: "memory")
; #define PG8_WAIT_L(n) asm volatile("s_waitcnt lgkmcnt(" #n ")" ::: "memory")
; template <class Epi>
; __device__ __forceinline__ void gemm_phase(LAS unsigned char* lds, const Gemm g, const Epi& E) {
;     ...
;             PG8_LDB(B0, 0, 0); PG8_LDB(B1, 0, 1); PG8_SCHED; PG8_LDA(At, 0, 0); PG8_STAGE(PG8_SA(1, 1), a1 + hstep, voffA);
;             PG8_WAIT_V(8); PG8_WAIT_L(0); PG8_BAR; PG8_MMA(0, 0, At, B0); PG8_MMA(0, 1, At, B1); PG8_BAR; PG8_SCHED;
;             PG8_LDA(At, 0, 1); PG8_STAGE(PG8_SB(0, 0), b2, voffA); PG8_STAGE(PG8_SB(0, 1), b2 + hstep, voffA); PG8_STAGE(PG8_SA(0, 0), a2, voffA);
;             PG8_WAIT_V(8); PG8_WAIT_L(0); PG8_BAR; PG8_MMA(1, 0, At, B0); PG8_MMA(1, 1, At, B1); PG8_BAR; PG8_SCHED;
;             PG8_LDB(B0, 1, 0); PG8_LDB(B1, 1, 1); PG8_SCHED; PG8_LDA(At, 1, 0); PG8_STAGE(PG8_SA(0, 1), a2 + hstep, voffA);
;             PG8_WAIT_V(8); PG8_WAIT_L(0); PG8_BAR; PG8_MMA(0, 0, At, B0); PG8_MMA(0, 1, At, B1); PG8_BAR; PG8_SCHED;
;             PG8_LDA(At, 1, 1); PG8_STAGE(PG8_SB(1, 0), b3, voffA); PG8_STAGE(PG8_SB(1, 1), b3 + hstep, voffA); PG8_STAGE(PG8_SA(1, 0), a3, voffA);
;             PG8_WAIT_V(8); PG8_WAIT_L(0); PG8_BAR; PG8_MMA(1, 0, At, B0); PG8_MMA(1, 1, At, B1); PG8_BAR; PG8_SCHED;
	s_add_i32 s10, s25, s26
	v_lshl_add_u64 v[164:165], v[164:165], 0, s[80:81]
	s_mov_b32 m0, s10
	ds_read_b128 v[202:205], v167 offset:49152
	ds_read_b128 v[206:209], v167 offset:50176
	ds_read_b128 v[210:213], v167 offset:51200
	ds_read_b128 v[214:217], v167 offset:52224
	ds_read_b128 v[218:221], v167 offset:53248
	ds_read_b128 v[222:225], v167 offset:54272
	ds_read_b128 v[226:229], v167 offset:55296
	ds_read_b128 v[230:233], v167 offset:56320
	global_load_lds_dwordx4 v[164:165], off
	s_add_i32 m0, s10, 0x2000
	s_add_u32 s4, s4, 0x40080
	v_lshl_add_u64 v[164:165], v[168:169], 0, s[80:81]
	s_addc_u32 s5, s5, 0
	s_add_i32 s10, s79, s26
	global_load_lds_dwordx4 v[164:165], off
	v_lshl_add_u64 v[164:165], s[4:5], 0, v[0:1]
	s_mov_b32 m0, s10
	s_nop 0
	global_load_lds_dwordx4 v[164:165], off
	v_lshl_add_u64 v[164:165], s[4:5], 0, v[146:147]
	s_add_i32 m0, s10, 0x2000
	s_nop 0
	global_load_lds_dwordx4 v[164:165], off
	v_lshl_add_u64 v[164:165], v[234:235], 0, s[80:81]
	s_mov_b32 m0, s37
	s_nop 0
	global_load_lds_dwordx4 v[164:165], off
	v_lshl_add_u64 v[164:165], v[236:237], 0, s[80:81]
	s_mov_b32 m0, s93
	s_nop 0
	global_load_lds_dwordx4 v[164:165], off
	s_waitcnt vmcnt(8)
	s_waitcnt lgkmcnt(0)
	s_barrier
	s_waitcnt lgkmcnt(0)
	v_mfma_f32_16x16x32_bf16 v[58:61], v[130:133], v[202:205], v[58:61]
	v_mfma_f32_16x16x32_bf16 v[62:65], v[152:155], v[202:205], v[62:65]
	v_mfma_f32_16x16x32_bf16 v[42:45], v[130:133], v[210:213], v[42:45]
	v_mfma_f32_16x16x32_bf16 v[46:49], v[152:155], v[210:213], v[46:49]
	v_mfma_f32_16x16x32_bf16 v[26:29], v[130:133], v[218:221], v[26:29]
	v_mfma_f32_16x16x32_bf16 v[30:33], v[152:155], v[218:221], v[30:33]
	v_mfma_f32_16x16x32_bf16 v[10:13], v[130:133], v[226:229], v[10:13]
	v_mfma_f32_16x16x32_bf16 v[14:17], v[152:155], v[226:229], v[14:17]
	v_mfma_f32_16x16x32_bf16 v[58:61], v[134:137], v[206:209], v[58:61]
	v_mfma_f32_16x16x32_bf16 v[62:65], v[156:159], v[206:209], v[62:65]
	v_mfma_f32_16x16x32_bf16 v[42:45], v[134:137], v[214:217], v[42:45]
	v_mfma_f32_16x16x32_bf16 v[46:49], v[156:159], v[214:217], v[46:49]
	v_mfma_f32_16x16x32_bf16 v[26:29], v[134:137], v[222:225], v[26:29]
	v_mfma_f32_16x16x32_bf16 v[30:33], v[156:159], v[222:225], v[30:33]
	v_mfma_f32_16x16x32_bf16 v[10:13], v[134:137], v[230:233], v[10:13]
	v_mfma_f32_16x16x32_bf16 v[14:17], v[156:159], v[230:233], v[14:17]
	v_mfma_f32_16x16x32_bf16 v[50:53], v[160:163], v[202:205], v[50:53]
	v_mfma_f32_16x16x32_bf16 v[54:57], v[194:197], v[202:205], v[54:57]
	v_mfma_f32_16x16x32_bf16 v[34:37], v[160:163], v[210:213], v[34:37]
	v_mfma_f32_16x16x32_bf16 v[38:41], v[194:197], v[210:213], v[38:41]
	v_mfma_f32_16x16x32_bf16 v[18:21], v[160:163], v[218:221], v[18:21]
	v_mfma_f32_16x16x32_bf16 v[22:25], v[194:197], v[218:221], v[22:25]
	v_mfma_f32_16x16x32_bf16 v[6:9], v[160:163], v[226:229], v[6:9]
	v_mfma_f32_16x16x32_bf16 v[2:5], v[194:197], v[226:229], v[2:5]
	v_mfma_f32_16x16x32_bf16 v[50:53], v[190:193], v[206:209], v[50:53]
	v_mfma_f32_16x16x32_bf16 v[54:57], v[198:201], v[206:209], v[54:57]
	v_mfma_f32_16x16x32_bf16 v[34:37], v[190:193], v[214:217], v[34:37]
	v_mfma_f32_16x16x32_bf16 v[38:41], v[198:201], v[214:217], v[38:41]
	v_mfma_f32_16x16x32_bf16 v[18:21], v[190:193], v[222:225], v[18:21]
	v_mfma_f32_16x16x32_bf16 v[22:25], v[198:201], v[222:225], v[22:25]
	v_mfma_f32_16x16x32_bf16 v[6:9], v[190:193], v[230:233], v[6:9]
	v_mfma_f32_16x16x32_bf16 v[2:5], v[198:201], v[230:233], v[2:5]
	s_barrier
	s_add_u32 s8, s8, 0x100
	s_addc_u32 s9, s9, 0
	s_add_u32 s71, s71, 0x100
	s_addc_u32 s75, s75, 0
	s_cmp_ge_i32 s78, s72
	s_mov_b32 s4, s78
	s_cbranch_scc0 .LBB0_95
	s_branch .Lk1_exit

; #define PG8_STAGE(bufoff, gbase, voff) do { _Pragma("unroll") for (int _i = 0; _i < 2; ++_i) \
;         __builtin_amdgcn_global_load_lds((const unsigned*)((const char*)(gbase) + (voff)[_i]), (LAS unsigned*)(lds + (bufoff) + ldsw + _i * 8192), 16, 0, 0); } while (0)
; #define PG8_LDA(dst, b, h) do { _Pragma("unroll") for (int m = 0; m < 4; ++m) _Pragma("unroll") for (int k = 0; k < 2; ++k) dst[m][k] = *(const LAS bf16x8*)(lds + PG8_SA(b, h) + aoff + m * 2048 + k * 1024); } while (0)
; #define PG8_LDB(dst, b, h) do { _Pragma("unroll") for (int n = 0; n < 2; ++n) _Pragma("unroll") for (int k = 0; k < 2; ++k) dst[n][k] = *(const LAS bf16x8*)(lds + PG8_SB(b, h) + boff + n * 2048 + k * 1024); } while (0)
; #define PG8_MMA(ai, bj, At, Bt) do { __builtin_amdgcn_s_setprio(1); _Pragma("unroll") for (int m = 0; m < 4; ++m) _Pragma("unroll") for (int n = 0; n < 2; ++n) _Pragma("unroll") for (int k = 0; k < 2; ++k) \
;         acc[ai][bj][m][n] = __builtin_amdgcn_mfma_f32_16x16x32_bf16(Bt[n][k], At[m][k], acc[ai][bj][m][n], 0, 0, 0); __builtin_amdgcn_s_setprio(0); } while (0)
; #define PG8_WAIT_V(n) asm volatile("s_waitcnt vmcnt(" #n ")" ::: "memory")
; #define PG8_BAR __builtin_amdgcn_s_barrier()
; template <class Epi>
; __device__ __forceinline__ void gemm_phase(LAS unsigned char* lds, const Gemm g, const Epi& E) {
;     ...
;         const char* nA = has_next ? (const char*)((nxt.sub & 1) ? g.A1 : g.A0) + (size_t)nxt.pm * tstep + (size_t)nxt.kt0 * kstep : cA; const char* nB = has_next ? (const char*)((nxt.sub & 1) ? g.B1 : g.B0) + (size_t)nxt.pn * tstep + (size_t)nxt.kt0 * kstep : cB;
;         const int nt = cur.nt;
;         for (int t = 0; t < nt; t += 2) {
;             const bool last = (t == nt - 2);
;             const char* a1 = cA + (size_t)(t + 1) * kstep;
;             const char* a2 = last ? nA : cA + (size_t)(t + 2) * kstep; const char* b2 = last ? nB : cB + (size_t)(t + 2) * kstep;
;             const char* a3 = a2 + kstep; const char* b3 = b2 + kstep;
;             PG8_LDB(B0, 0, 0); PG8_LDB(B1, 0, 1); PG8_SCHED; PG8_LDA(At, 0, 0); PG8_STAGE(PG8_SA(1, 1), a1 + hstep, voffA);
;             PG8_WAIT_V(8); PG8_WAIT_L(0); PG8_BAR; PG8_MMA(0, 0, At, B0); PG8_MMA(0, 1, At, B1); PG8_BAR; PG8_SCHED;
;             PG8_LDA(At, 0, 1); PG8_STAGE(PG8_SB(0, 0), b2, voffA); PG8_STAGE(PG8_SB(0, 1), b2 + hstep, voffA); PG8_STAGE(PG8_SA(0, 0), a2, voffA);
.LBB0_95:
	s_add_i32 s78, s4, 2
	s_add_u32 s5, s8, 0xfffc0080
	s_addc_u32 s10, s9, -1
	s_cmp_eq_u32 s69, s4
	s_cselect_b32 s11, s2, s10
	s_cselect_b32 s10, s12, s5
	s_cselect_b32 s5, s13, s75
	s_cselect_b32 s4, s15, s71
	s_add_i32 s25, 0, 0x14000
	v_add_u32_e32 v156, s21, v166
	v_add_u32_e32 v164, s25, v166
	ds_read_b128 v[130:133], v156
	ds_read_b128 v[134:137], v156 offset:1024
	ds_read_b128 v[152:155], v156 offset:2048
	ds_read_b128 v[156:159], v156 offset:3072
	ds_read_b128 v[160:163], v164
	ds_read_b128 v[190:193], v164 offset:1024
	ds_read_b128 v[194:197], v164 offset:2048
	ds_read_b128 v[198:201], v164 offset:3072
	v_lshl_add_u64 v[164:165], s[8:9], 0, v[148:149]
	s_add_i32 m0, s53, 0xc000
	ds_read_b128 v[202:205], v167
	ds_read_b128 v[206:209], v167 offset:1024
	ds_read_b128 v[210:213], v167 offset:2048
	ds_read_b128 v[214:217], v167 offset:3072
	ds_read_b128 v[218:221], v167 offset:4096
	ds_read_b128 v[222:225], v167 offset:5120
	ds_read_b128 v[226:229], v167 offset:6144
	ds_read_b128 v[230:233], v167 offset:7168
	global_load_lds_dwordx4 v[164:165], off
	v_lshl_add_u64 v[164:165], s[8:9], 0, v[150:151]
	s_add_i32 m0, s53, 0xe000
	s_nop 0
	global_load_lds_dwordx4 v[164:165], off
	s_waitcnt vmcnt(8)
	s_waitcnt lgkmcnt(0)
	s_barrier
	s_waitcnt lgkmcnt(0)
	v_mfma_f32_16x16x32_bf16 v[122:125], v[130:133], v[202:205], v[122:125]
	v_mfma_f32_16x16x32_bf16 v[126:129], v[152:155], v[202:205], v[126:129]
	v_mfma_f32_16x16x32_bf16 v[106:109], v[130:133], v[210:213], v[106:109]
	v_mfma_f32_16x16x32_bf16 v[110:113], v[152:155], v[210:213], v[110:113]
	v_mfma_f32_16x16x32_bf16 v[90:93], v[130:133], v[218:221], v[90:93]
	v_mfma_f32_16x16x32_bf16 v[94:97], v[152:155], v[218:221], v[94:97]
	v_mfma_f32_16x16x32_bf16 v[74:77], v[130:133], v[226:229], v[74:77]
	v_mfma_f32_16x16x32_bf16 v[78:81], v[152:155], v[226:229], v[78:81]
	v_mfma_f32_16x16x32_bf16 v[122:125], v[134:137], v[206:209], v[122:125]
	v_mfma_f32_16x16x32_bf16 v[126:129], v[156:159], v[206:209], v[126:129]
	v_mfma_f32_16x16x32_bf16 v[106:109], v[134:137], v[214:217], v[106:109]
	v_mfma_f32_16x16x32_bf16 v[110:113], v[156:159], v[214:217], v[110:113]
	v_mfma_f32_16x16x32_bf16 v[90:93], v[134:137], v[222:225], v[90:93]
	v_mfma_f32_16x16x32_bf16 v[94:97], v[156:159], v[222:225], v[94:97]
	v_mfma_f32_16x16x32_bf16 v[74:77], v[134:137], v[230:233], v[74:77]
	v_mfma_f32_16x16x32_bf16 v[78:81], v[156:159], v[230:233], v[78:81]
	v_mfma_f32_16x16x32_bf16 v[114:117], v[160:163], v[202:205], v[114:117]
	v_mfma_f32_16x16x32_bf16 v[118:121], v[194:197], v[202:205], v[118:121]
	v_mfma_f32_16x16x32_bf16 v[98:101], v[160:163], v[210:213], v[98:101]
	v_mfma_f32_16x16x32_bf16 v[102:105], v[194:197], v[210:213], v[102:105]
	v_mfma_f32_16x16x32_bf16 v[82:85], v[160:163], v[218:221], v[82:85]
	v_mfma_f32_16x16x32_bf16 v[86:89], v[194:197], v[218:221], v[86:89]
	v_mfma_f32_16x16x32_bf16 v[66:69], v[160:163], v[226:229], v[66:69]
	v_mfma_f32_16x16x32_bf16 v[70:73], v[194:197], v[226:229], v[70:73]
	v_mfma_f32_16x16x32_bf16 v[114:117], v[190:193], v[206:209], v[114:117]
	v_mfma_f32_16x16x32_bf16 v[118:121], v[198:201], v[206:209], v[118:121]
	v_mfma_f32_16x16x32_bf16 v[98:101], v[190:193], v[214:217], v[98:101]
	v_mfma_f32_16x16x32_bf16 v[102:105], v[198:201], v[214:217], v[102:105]
	v_mfma_f32_16x16x32_bf16 v[82:85], v[190:193], v[222:225], v[82:85]
	v_mfma_f32_16x16x32_bf16 v[86:89], v[198:201], v[222:225], v[86:89]
	v_mfma_f32_16x16x32_bf16 v[66:69], v[190:193], v[230:233], v[66:69]
	v_mfma_f32_16x16x32_bf16 v[70:73], v[198:201], v[230:233], v[70:73]
	s_barrier
	s_add_i32 s79, s21, s26
	v_lshl_add_u64 v[164:165], s[4:5], 0, v[0:1]
	s_mov_b32 m0, s79
	ds_read_b128 v[202:205], v167 offset:16384
	ds_read_b128 v[206:209], v167 offset:17408
	ds_read_b128 v[210:213], v167 offset:18432
	ds_read_b128 v[214:217], v167 offset:19456
	ds_read_b128 v[218:221], v167 offset:20480
	ds_read_b128 v[222:225], v167 offset:21504
	ds_read_b128 v[226:229], v167 offset:22528
	ds_read_b128 v[230:233], v167 offset:23552
	global_load_lds_dwordx4 v[164:165], off
	s_add_i32 m0, s79, 0x2000
	s_add_u32 vcc_lo, s4, 0x40000
	v_lshl_add_u64 v[168:169], s[4:5], 0, v[146:147]
	s_addc_u32 vcc_hi, s5, 0
	s_add_i32 s25, s25, s26
	global_load_lds_dwordx4 v[168:169], off
	v_lshl_add_u64 v[234:235], vcc, 0, v[0:1]
	s_mov_b32 m0, s25
	v_lshl_add_u64 v[236:237], s[10:11], 0, v[146:147]
	global_load_lds_dwordx4 v[234:235], off
	v_lshl_add_u64 v[234:235], vcc, 0, v[146:147]
	s_add_i32 m0, s25, 0x2000
	s_nop 0
	global_load_lds_dwordx4 v[234:235], off
	v_lshl_add_u64 v[234:235], s[10:11], 0, v[0:1]
	s_mov_b32 m0, s53
	s_nop 0
	global_load_lds_dwordx4 v[234:235], off
	s_mov_b32 m0, s73
	s_nop 0
	global_load_lds_dwordx4 v[236:237], off
	s_waitcnt vmcnt(8)
	s_waitcnt lgkmcnt(0)
	s_barrier
; #define PG8_STAGE(bufoff, gbase, voff) do { _Pragma("unroll") for (int _i = 0; _i < 2; ++_i) \
;         __builtin_amdgcn_global_load_lds((const unsigned*)((const char*)(gbase) + (voff)[_i]), (LAS unsigned*)(lds + (bufoff) + ldsw + _i * 8192), 16, 0, 0); } while (0)
; #define PG8_LDA(dst, b, h) do { _Pragma("unroll") for (int m = 0; m < 4; ++m) _Pragma("unroll") for (int k = 0; k < 2; ++k) dst[m][k] = *(const LAS bf16x8*)(lds + PG8_SA(b, h) + aoff + m * 2048 + k * 1024); } while (0)
; #define PG8_LDB(dst, b, h) do { _Pragma("unroll") for (int n = 0; n < 2; ++n) _Pragma("unroll") for (int k = 0; k < 2; ++k) dst[n][k] = *(const LAS bf16x8*)(lds + PG8_SB(b, h) + boff + n * 2048 + k * 1024); } while (0)
; #define PG8_MMA(ai, bj, At, Bt) do { __builtin_amdgcn_s_setprio(1); _Pragma("unroll") for (int m = 0; m < 4; ++m) _Pragma("unroll") for (int n = 0; n < 2; ++n) _Pragma("unroll") for (int k = 0; k < 2; ++k) \
;         acc[ai][bj][m][n] = __builtin_amdgcn_mfma_f32_16x16x32_bf16(Bt[n][k], At[m][k], acc[ai][bj][m][n], 0, 0, 0); __builtin_amdgcn_s_setprio(0); } while (0)
; #define PG8_WAIT_V(n) asm volatile("s_waitcnt vmcnt(" #n ")" ::: "memory")
; #define PG8_WAIT_L(n) asm volatile("s_waitcnt lgkmcnt(" #n ")" ::: "memory")
; #define PG8_BAR __builtin_amdgcn_s_barrier()
; #define PG8_SCHED __builtin_amdgcn_sched_barrier(0)
; template <class Epi>
; __device__ __forceinline__ void gemm_phase(LAS unsigned char* lds, const Gemm g, const Epi& E) {
;     ...
;             PG8_WAIT_V(8); PG8_WAIT_L(0); PG8_BAR; PG8_MMA(1, 0, At, B0); PG8_MMA(1, 1, At, B1); PG8_BAR; PG8_SCHED;
;             PG8_LDB(B0, 1, 0); PG8_LDB(B1, 1, 1); PG8_SCHED; PG8_LDA(At, 1, 0); PG8_STAGE(PG8_SA(0, 1), a2 + hstep, voffA);
;             PG8_WAIT_V(8); PG8_WAIT_L(0); PG8_BAR; PG8_MMA(0, 0, At, B0); PG8_MMA(0, 1, At, B1); PG8_BAR; PG8_SCHED;
;             PG8_LDA(At, 1, 1); PG8_STAGE(PG8_SB(1, 0), b3, voffA); PG8_STAGE(PG8_SB(1, 1), b3 + hstep, voffA); PG8_STAGE(PG8_SA(1, 0), a3, voffA);
	s_waitcnt lgkmcnt(0)
	v_mfma_f32_16x16x32_bf16 v[58:61], v[130:133], v[202:205], v[58:61]
	v_mfma_f32_16x16x32_bf16 v[62:65], v[152:155], v[202:205], v[62:65]
	v_mfma_f32_16x16x32_bf16 v[42:45], v[130:133], v[210:213], v[42:45]
	v_mfma_f32_16x16x32_bf16 v[46:49], v[152:155], v[210:213], v[46:49]
	v_mfma_f32_16x16x32_bf16 v[26:29], v[130:133], v[218:221], v[26:29]
	v_mfma_f32_16x16x32_bf16 v[30:33], v[152:155], v[218:221], v[30:33]
	v_mfma_f32_16x16x32_bf16 v[10:13], v[130:133], v[226:229], v[10:13]
	v_mfma_f32_16x16x32_bf16 v[14:17], v[152:155], v[226:229], v[14:17]
	v_mfma_f32_16x16x32_bf16 v[58:61], v[134:137], v[206:209], v[58:61]
	v_mfma_f32_16x16x32_bf16 v[62:65], v[156:159], v[206:209], v[62:65]
	v_mfma_f32_16x16x32_bf16 v[42:45], v[134:137], v[214:217], v[42:45]
	v_mfma_f32_16x16x32_bf16 v[46:49], v[156:159], v[214:217], v[46:49]
	v_mfma_f32_16x16x32_bf16 v[26:29], v[134:137], v[222:225], v[26:29]
	v_mfma_f32_16x16x32_bf16 v[30:33], v[156:159], v[222:225], v[30:33]
	v_mfma_f32_16x16x32_bf16 v[10:13], v[134:137], v[230:233], v[10:13]
	v_mfma_f32_16x16x32_bf16 v[14:17], v[156:159], v[230:233], v[14:17]
	v_mfma_f32_16x16x32_bf16 v[50:53], v[160:163], v[202:205], v[50:53]
	v_mfma_f32_16x16x32_bf16 v[54:57], v[194:197], v[202:205], v[54:57]
	v_mfma_f32_16x16x32_bf16 v[34:37], v[160:163], v[210:213], v[34:37]
	v_mfma_f32_16x16x32_bf16 v[38:41], v[194:197], v[210:213], v[38:41]
	v_mfma_f32_16x16x32_bf16 v[18:21], v[160:163], v[218:221], v[18:21]
	v_mfma_f32_16x16x32_bf16 v[22:25], v[194:197], v[218:221], v[22:25]
	v_mfma_f32_16x16x32_bf16 v[6:9], v[160:163], v[226:229], v[6:9]
	v_mfma_f32_16x16x32_bf16 v[2:5], v[194:197], v[226:229], v[2:5]
	v_mfma_f32_16x16x32_bf16 v[50:53], v[190:193], v[206:209], v[50:53]
	v_mfma_f32_16x16x32_bf16 v[54:57], v[198:201], v[206:209], v[54:57]
	v_mfma_f32_16x16x32_bf16 v[34:37], v[190:193], v[214:217], v[34:37]
	v_mfma_f32_16x16x32_bf16 v[38:41], v[198:201], v[214:217], v[38:41]
	v_mfma_f32_16x16x32_bf16 v[18:21], v[190:193], v[222:225], v[18:21]
	v_mfma_f32_16x16x32_bf16 v[22:25], v[198:201], v[222:225], v[22:25]
	v_mfma_f32_16x16x32_bf16 v[6:9], v[190:193], v[230:233], v[6:9]
	v_mfma_f32_16x16x32_bf16 v[2:5], v[198:201], v[230:233], v[2:5]
	s_barrier
	s_add_i32 s25, 0, 0x18000
	s_add_i32 s79, 0, 0x1c000
	v_add_u32_e32 v156, s25, v166
	v_add_u32_e32 v189, s79, v166
	ds_read_b128 v[130:133], v156
	ds_read_b128 v[134:137], v156 offset:1024
	ds_read_b128 v[152:155], v156 offset:2048
	ds_read_b128 v[156:159], v156 offset:3072
	ds_read_b128 v[160:163], v189
	ds_read_b128 v[190:193], v189 offset:1024
	ds_read_b128 v[194:197], v189 offset:2048
	ds_read_b128 v[198:201], v189 offset:3072
	s_add_u32 s10, s10, 0x40000
	s_addc_u32 s11, s11, 0
	s_mov_b32 m0, s76
	v_lshl_add_u64 v[238:239], s[10:11], 0, v[0:1]
	ds_read_b128 v[202:205], v167 offset:32768
	ds_read_b128 v[206:209], v167 offset:33792
	ds_read_b128 v[210:213], v167 offset:34816
	ds_read_b128 v[214:217], v167 offset:35840
	ds_read_b128 v[218:221], v167 offset:36864
	ds_read_b128 v[222:225], v167 offset:37888
	ds_read_b128 v[226:229], v167 offset:38912
	ds_read_b128 v[230:233], v167 offset:39936
	global_load_lds_dwordx4 v[238:239], off
	v_lshl_add_u64 v[238:239], s[10:11], 0, v[146:147]
	s_mov_b32 m0, s77
	s_nop 0
	global_load_lds_dwordx4 v[238:239], off
	s_waitcnt vmcnt(8)
	s_waitcnt lgkmcnt(0)
	s_barrier
	s_waitcnt lgkmcnt(0)
	v_mfma_f32_16x16x32_bf16 v[122:125], v[130:133], v[202:205], v[122:125]
	v_mfma_f32_16x16x32_bf16 v[126:129], v[152:155], v[202:205], v[126:129]
	v_mfma_f32_16x16x32_bf16 v[106:109], v[130:133], v[210:213], v[106:109]
	v_mfma_f32_16x16x32_bf16 v[110:113], v[152:155], v[210:213], v[110:113]
	v_mfma_f32_16x16x32_bf16 v[90:93], v[130:133], v[218:221], v[90:93]
	v_mfma_f32_16x16x32_bf16 v[94:97], v[152:155], v[218:221], v[94:97]
	v_mfma_f32_16x16x32_bf16 v[74:77], v[130:133], v[226:229], v[74:77]
	v_mfma_f32_16x16x32_bf16 v[78:81], v[152:155], v[226:229], v[78:81]
	v_mfma_f32_16x16x32_bf16 v[122:125], v[134:137], v[206:209], v[122:125]
	v_mfma_f32_16x16x32_bf16 v[126:129], v[156:159], v[206:209], v[126:129]
	v_mfma_f32_16x16x32_bf16 v[106:109], v[134:137], v[214:217], v[106:109]
	v_mfma_f32_16x16x32_bf16 v[110:113], v[156:159], v[214:217], v[110:113]
	v_mfma_f32_16x16x32_bf16 v[90:93], v[134:137], v[222:225], v[90:93]
	v_mfma_f32_16x16x32_bf16 v[94:97], v[156:159], v[222:225], v[94:97]
	v_mfma_f32_16x16x32_bf16 v[74:77], v[134:137], v[230:233], v[74:77]
	v_mfma_f32_16x16x32_bf16 v[78:81], v[156:159], v[230:233], v[78:81]
	v_mfma_f32_16x16x32_bf16 v[114:117], v[160:163], v[202:205], v[114:117]
	v_mfma_f32_16x16x32_bf16 v[118:121], v[194:197], v[202:205], v[118:121]
	v_mfma_f32_16x16x32_bf16 v[98:101], v[160:163], v[210:213], v[98:101]
	v_mfma_f32_16x16x32_bf16 v[102:105], v[194:197], v[210:213], v[102:105]
	v_mfma_f32_16x16x32_bf16 v[82:85], v[160:163], v[218:221], v[82:85]
	v_mfma_f32_16x16x32_bf16 v[86:89], v[194:197], v[218:221], v[86:89]
	v_mfma_f32_16x16x32_bf16 v[66:69], v[160:163], v[226:229], v[66:69]
	v_mfma_f32_16x16x32_bf16 v[70:73], v[194:197], v[226:229], v[70:73]
	v_mfma_f32_16x16x32_bf16 v[114:117], v[190:193], v[206:209], v[114:117]
	v_mfma_f32_16x16x32_bf16 v[118:121], v[198:201], v[206:209], v[118:121]
	v_mfma_f32_16x16x32_bf16 v[98:101], v[190:193], v[214:217], v[98:101]
	v_mfma_f32_16x16x32_bf16 v[102:105], v[198:201], v[214:217], v[102:105]
	v_mfma_f32_16x16x32_bf16 v[82:85], v[190:193], v[222:225], v[82:85]
	v_mfma_f32_16x16x32_bf16 v[86:89], v[198:201], v[222:225], v[86:89]
	v_mfma_f32_16x16x32_bf16 v[66:69], v[190:193], v[230:233], v[66:69]
	v_mfma_f32_16x16x32_bf16 v[70:73], v[198:201], v[230:233], v[70:73]
	s_barrier
; #define PG8_STAGE(bufoff, gbase, voff) do { _Pragma("unroll") for (int _i = 0; _i < 2; ++_i) \
;         __builtin_amdgcn_global_load_lds((const unsigned*)((const char*)(gbase) + (voff)[_i]), (LAS unsigned*)(lds + (bufoff) + ldsw + _i * 8192), 16, 0, 0); } while (0)
; #define PG8_LDA(dst, b, h) do { _Pragma("unroll") for (int m = 0; m < 4; ++m) _Pragma("unroll") for (int k = 0; k < 2; ++k) dst[m][k] = *(const LAS bf16x8*)(lds + PG8_SA(b, h) + aoff + m * 2048 + k * 1024); } while (0)
; #define PG8_MMA(ai, bj, At, Bt) do { __builtin_amdgcn_s_setprio(1); _Pragma("unroll") for (int m = 0; m < 4; ++m) _Pragma("unroll") for (int n = 0; n < 2; ++n) _Pragma("unroll") for (int k = 0; k < 2; ++k) \
;         acc[ai][bj][m][n] = __builtin_amdgcn_mfma_f32_16x16x32_bf16(Bt[n][k], At[m][k], acc[ai][bj][m][n], 0, 0, 0); __builtin_amdgcn_s_setprio(0); } while (0)
; #define PG8_WAIT_V(n) asm volatile("s_waitcnt vmcnt(" #n ")" ::: "memory")
; #define PG8_WAIT_L(n) asm volatile("s_waitcnt lgkmcnt(" #n ")" ::: "memory")
; #define PG8_BAR __builtin_amdgcn_s_barrier()
; #define PG8_SCHED __builtin_amdgcn_sched_barrier(0)
; template <class Epi>
; __device__ __forceinline__ void gemm_phase(LAS unsigned char* lds, const Gemm g, const Epi& E) {
;     ...
;             PG8_LDA(At, 1, 1); PG8_STAGE(PG8_SB(1, 0), b3, voffA); PG8_STAGE(PG8_SB(1, 1), b3 + hstep, voffA); PG8_STAGE(PG8_SA(1, 0), a3, voffA);
;             PG8_WAIT_V(8); PG8_WAIT_L(0); PG8_BAR; PG8_MMA(1, 0, At, B0); PG8_MMA(1, 1, At, B1); PG8_BAR; PG8_SCHED;
	s_add_i32 s10, s25, s26
	v_lshl_add_u64 v[164:165], v[164:165], 0, s[80:81]
	s_mov_b32 m0, s10
	ds_read_b128 v[202:205], v167 offset:49152
	ds_read_b128 v[206:209], v167 offset:50176
	ds_read_b128 v[210:213], v167 offset:51200
	ds_read_b128 v[214:217], v167 offset:52224
	ds_read_b128 v[218:221], v167 offset:53248
	ds_read_b128 v[222:225], v167 offset:54272
	ds_read_b128 v[226:229], v167 offset:55296
	ds_read_b128 v[230:233], v167 offset:56320
	global_load_lds_dwordx4 v[164:165], off
	s_add_i32 m0, s10, 0x2000
	s_add_u32 s4, s4, 0x40080
	v_lshl_add_u64 v[164:165], v[168:169], 0, s[80:81]
	s_addc_u32 s5, s5, 0
	s_add_i32 s10, s79, s26
	global_load_lds_dwordx4 v[164:165], off
	v_lshl_add_u64 v[164:165], s[4:5], 0, v[0:1]
	s_mov_b32 m0, s10
	s_nop 0
	global_load_lds_dwordx4 v[164:165], off
	v_lshl_add_u64 v[164:165], s[4:5], 0, v[146:147]
	s_add_i32 m0, s10, 0x2000
	s_nop 0
	global_load_lds_dwordx4 v[164:165], off
	v_lshl_add_u64 v[164:165], v[234:235], 0, s[80:81]
	s_mov_b32 m0, s37
	s_nop 0
	global_load_lds_dwordx4 v[164:165], off
	v_lshl_add_u64 v[164:165], v[236:237], 0, s[80:81]
	s_mov_b32 m0, s93
	s_nop 0
	global_load_lds_dwordx4 v[164:165], off
	s_waitcnt vmcnt(8)
	s_waitcnt lgkmcnt(0)
	s_barrier
	s_waitcnt lgkmcnt(0)
	v_mfma_f32_16x16x32_bf16 v[58:61], v[130:133], v[202:205], v[58:61]
	v_mfma_f32_16x16x32_bf16 v[62:65], v[152:155], v[202:205], v[62:65]
	v_mfma_f32_16x16x32_bf16 v[42:45], v[130:133], v[210:213], v[42:45]
	v_mfma_f32_16x16x32_bf16 v[46:49], v[152:155], v[210:213], v[46:49]
	v_mfma_f32_16x16x32_bf16 v[26:29], v[130:133], v[218:221], v[26:29]
	v_mfma_f32_16x16x32_bf16 v[30:33], v[152:155], v[218:221], v[30:33]
	v_mfma_f32_16x16x32_bf16 v[10:13], v[130:133], v[226:229], v[10:13]
	v_mfma_f32_16x16x32_bf16 v[14:17], v[152:155], v[226:229], v[14:17]
	v_mfma_f32_16x16x32_bf16 v[58:61], v[134:137], v[206:209], v[58:61]
	v_mfma_f32_16x16x32_bf16 v[62:65], v[156:159], v[206:209], v[62:65]
	v_mfma_f32_16x16x32_bf16 v[42:45], v[134:137], v[214:217], v[42:45]
	v_mfma_f32_16x16x32_bf16 v[46:49], v[156:159], v[214:217], v[46:49]
	v_mfma_f32_16x16x32_bf16 v[26:29], v[134:137], v[222:225], v[26:29]
	v_mfma_f32_16x16x32_bf16 v[30:33], v[156:159], v[222:225], v[30:33]
	v_mfma_f32_16x16x32_bf16 v[10:13], v[134:137], v[230:233], v[10:13]
	v_mfma_f32_16x16x32_bf16 v[14:17], v[156:159], v[230:233], v[14:17]
	v_mfma_f32_16x16x32_bf16 v[50:53], v[160:163], v[202:205], v[50:53]
	v_mfma_f32_16x16x32_bf16 v[54:57], v[194:197], v[202:205], v[54:57]
	v_mfma_f32_16x16x32_bf16 v[34:37], v[160:163], v[210:213], v[34:37]
	v_mfma_f32_16x16x32_bf16 v[38:41], v[194:197], v[210:213], v[38:41]
	v_mfma_f32_16x16x32_bf16 v[18:21], v[160:163], v[218:221], v[18:21]
	v_mfma_f32_16x16x32_bf16 v[22:25], v[194:197], v[218:221], v[22:25]
	v_mfma_f32_16x16x32_bf16 v[6:9], v[160:163], v[226:229], v[6:9]
	v_mfma_f32_16x16x32_bf16 v[2:5], v[194:197], v[226:229], v[2:5]
	v_mfma_f32_16x16x32_bf16 v[50:53], v[190:193], v[206:209], v[50:53]
	v_mfma_f32_16x16x32_bf16 v[54:57], v[198:201], v[206:209], v[54:57]
	v_mfma_f32_16x16x32_bf16 v[34:37], v[190:193], v[214:217], v[34:37]
	v_mfma_f32_16x16x32_bf16 v[38:41], v[198:201], v[214:217], v[38:41]
	v_mfma_f32_16x16x32_bf16 v[18:21], v[190:193], v[222:225], v[18:21]
	v_mfma_f32_16x16x32_bf16 v[22:25], v[198:201], v[222:225], v[22:25]
	v_mfma_f32_16x16x32_bf16 v[6:9], v[190:193], v[230:233], v[6:9]
	v_mfma_f32_16x16x32_bf16 v[2:5], v[198:201], v[230:233], v[2:5]
	s_barrier
	s_add_u32 s8, s8, 0x100
	s_addc_u32 s9, s9, 0
	s_add_u32 s71, s71, 0x100
	s_addc_u32 s75, s75, 0
	s_cmp_ge_i32 s78, s72
	s_mov_b32 s4, s78
	s_cbranch_scc0 .LBB0_95

; #define PG8_STAGE(bufoff, gbase, voff) do { _Pragma("unroll") for (int _i = 0; _i < 2; ++_i) \
;         __builtin_amdgcn_global_load_lds((const unsigned*)((const char*)(gbase) + (voff)[_i]), (LAS unsigned*)(lds + (bufoff) + ldsw + _i * 8192), 16, 0, 0); } while (0)
; #define PG8_LDA(dst, b, h) do { _Pragma("unroll") for (int m = 0; m < 4; ++m) _Pragma("unroll") for (int k = 0; k < 2; ++k) dst[m][k] = *(const LAS bf16x8*)(lds + PG8_SA(b, h) + aoff + m * 2048 + k * 1024); } while (0)
; #define PG8_LDB(dst, b, h) do { _Pragma("unroll") for (int n = 0; n < 2; ++n) _Pragma("unroll") for (int k = 0; k < 2; ++k) dst[n][k] = *(const LAS bf16x8*)(lds + PG8_SB(b, h) + boff + n * 2048 + k * 1024); } while (0)
; #define PG8_MMA(ai, bj, At, Bt) do { __builtin_amdgcn_s_setprio(1); _Pragma("unroll") for (int m = 0; m < 4; ++m) _Pragma("unroll") for (int n = 0; n < 2; ++n) _Pragma("unroll") for (int k = 0; k < 2; ++k) \
;         acc[ai][bj][m][n] = __builtin_amdgcn_mfma_f32_16x16x32_bf16(Bt[n][k], At[m][k], acc[ai][bj][m][n], 0, 0, 0); __builtin_amdgcn_s_setprio(0); } while (0)
; #define PG8_WAIT_V(n) asm volatile("s_waitcnt vmcnt(" #n ")" ::: "memory")
; #define PG8_BAR __builtin_amdgcn_s_barrier()
; template <class Epi>
; __device__ __forceinline__ void gemm_phase(LAS unsigned char* lds, const Gemm g, const Epi& E) {
;     ...
;         const char* nA = has_next ? (const char*)((nxt.sub & 1) ? g.A1 : g.A0) + (size_t)nxt.pm * tstep + (size_t)nxt.kt0 * kstep : cA; const char* nB = has_next ? (const char*)((nxt.sub & 1) ? g.B1 : g.B0) + (size_t)nxt.pn * tstep + (size_t)nxt.kt0 * kstep : cB;
;         const int nt = cur.nt;
;         for (int t = 0; t < nt; t += 2) {
;             const bool last = (t == nt - 2);
;             const char* a1 = cA + (size_t)(t + 1) * kstep;
;             const char* a2 = last ? nA : cA + (size_t)(t + 2) * kstep; const char* b2 = last ? nB : cB + (size_t)(t + 2) * kstep;
;             const char* a3 = a2 + kstep; const char* b3 = b2 + kstep;
;             PG8_LDB(B0, 0, 0); PG8_LDB(B1, 0, 1); PG8_SCHED; PG8_LDA(At, 0, 0); PG8_STAGE(PG8_SA(1, 1), a1 + hstep, voffA);
;             PG8_WAIT_V(8); PG8_WAIT_L(0); PG8_BAR; PG8_MMA(0, 0, At, B0); PG8_MMA(0, 1, At, B1); PG8_BAR; PG8_SCHED;
;             PG8_LDA(At, 0, 1); PG8_STAGE(PG8_SB(0, 0), b2, voffA); PG8_STAGE(PG8_SB(0, 1), b2 + hstep, voffA); PG8_STAGE(PG8_SA(0, 0), a2, voffA);
.LBB0_407:
	s_add_i32 vcc_lo, s4, 2
	s_add_u32 s25, s62, 0x80
	s_addc_u32 s5, s63, 0
	s_cmp_eq_u32 s7, s4
	s_cselect_b32 s5, s55, s5
	s_cselect_b32 s4, s54, s25
	v_add_u32_e32 v133, s21, v189
	s_cselect_b32 s73, s57, s53
	s_cselect_b32 s72, s56, s15
	s_add_i32 s25, 0, 0x14000
	ds_read_b128 v[148:151], v133
	ds_read_b128 v[152:155], v133 offset:1024
	ds_read_b128 v[156:159], v133 offset:2048
	ds_read_b128 v[160:163], v133 offset:3072
	v_add_u32_e32 v133, s25, v189
	ds_read_b128 v[164:167], v133
	ds_read_b128 v[192:195], v133 offset:1024
	ds_read_b128 v[196:199], v133 offset:2048
	ds_read_b128 v[200:203], v133 offset:3072
	v_lshl_add_u64 v[168:169], s[62:63], 0, v[136:137]
	s_add_i32 m0, s71, 0xc000
	ds_read_b128 v[204:207], v190
	ds_read_b128 v[208:211], v190 offset:1024
	ds_read_b128 v[212:215], v190 offset:2048
	ds_read_b128 v[216:219], v190 offset:3072
	ds_read_b128 v[220:223], v190 offset:4096
	ds_read_b128 v[224:227], v190 offset:5120
	ds_read_b128 v[228:231], v190 offset:6144
	ds_read_b128 v[232:235], v190 offset:7168
	global_load_lds_dwordx4 v[168:169], off
	v_lshl_add_u64 v[168:169], s[62:63], 0, v[146:147]
	s_add_i32 m0, s71, 0xe000
	s_nop 0
	global_load_lds_dwordx4 v[168:169], off
	s_waitcnt vmcnt(8)
	s_waitcnt lgkmcnt(0)
	s_barrier
	s_waitcnt lgkmcnt(0)
	v_mfma_f32_16x16x32_bf16 v[126:129], v[148:151], v[204:207], v[126:129]
	v_mfma_f32_16x16x32_bf16 v[122:125], v[156:159], v[204:207], v[122:125]
	v_mfma_f32_16x16x32_bf16 v[110:113], v[148:151], v[212:215], v[110:113]
	v_mfma_f32_16x16x32_bf16 v[106:109], v[156:159], v[212:215], v[106:109]
	v_mfma_f32_16x16x32_bf16 v[94:97], v[148:151], v[220:223], v[94:97]
	v_mfma_f32_16x16x32_bf16 v[90:93], v[156:159], v[220:223], v[90:93]
	v_mfma_f32_16x16x32_bf16 v[78:81], v[148:151], v[228:231], v[78:81]
	v_mfma_f32_16x16x32_bf16 v[74:77], v[156:159], v[228:231], v[74:77]
	v_mfma_f32_16x16x32_bf16 v[126:129], v[152:155], v[208:211], v[126:129]
	v_mfma_f32_16x16x32_bf16 v[122:125], v[160:163], v[208:211], v[122:125]
	v_mfma_f32_16x16x32_bf16 v[110:113], v[152:155], v[216:219], v[110:113]
	v_mfma_f32_16x16x32_bf16 v[106:109], v[160:163], v[216:219], v[106:109]
	v_mfma_f32_16x16x32_bf16 v[94:97], v[152:155], v[224:227], v[94:97]
	v_mfma_f32_16x16x32_bf16 v[90:93], v[160:163], v[224:227], v[90:93]
	v_mfma_f32_16x16x32_bf16 v[78:81], v[152:155], v[232:235], v[78:81]
	v_mfma_f32_16x16x32_bf16 v[74:77], v[160:163], v[232:235], v[74:77]
	v_mfma_f32_16x16x32_bf16 v[118:121], v[164:167], v[204:207], v[118:121]
	v_mfma_f32_16x16x32_bf16 v[114:117], v[196:199], v[204:207], v[114:117]
	v_mfma_f32_16x16x32_bf16 v[102:105], v[164:167], v[212:215], v[102:105]
	v_mfma_f32_16x16x32_bf16 v[98:101], v[196:199], v[212:215], v[98:101]
	v_mfma_f32_16x16x32_bf16 v[86:89], v[164:167], v[220:223], v[86:89]
	v_mfma_f32_16x16x32_bf16 v[82:85], v[196:199], v[220:223], v[82:85]
	v_mfma_f32_16x16x32_bf16 v[70:73], v[164:167], v[228:231], v[70:73]
	v_mfma_f32_16x16x32_bf16 v[66:69], v[196:199], v[228:231], v[66:69]
	v_mfma_f32_16x16x32_bf16 v[118:121], v[192:195], v[208:211], v[118:121]
	v_mfma_f32_16x16x32_bf16 v[114:117], v[200:203], v[208:211], v[114:117]
	v_mfma_f32_16x16x32_bf16 v[102:105], v[192:195], v[216:219], v[102:105]
	v_mfma_f32_16x16x32_bf16 v[98:101], v[200:203], v[216:219], v[98:101]
	v_mfma_f32_16x16x32_bf16 v[86:89], v[192:195], v[224:227], v[86:89]
	v_mfma_f32_16x16x32_bf16 v[82:85], v[200:203], v[224:227], v[82:85]
	v_mfma_f32_16x16x32_bf16 v[70:73], v[192:195], v[232:235], v[70:73]
	v_mfma_f32_16x16x32_bf16 v[66:69], v[200:203], v[232:235], v[66:69]
	s_barrier
	s_add_i32 vcc_hi, s21, s37
	v_lshl_add_u64 v[168:169], s[72:73], 0, v[0:1]
	s_mov_b32 m0, vcc_hi
	ds_read_b128 v[204:207], v190 offset:16384
	ds_read_b128 v[208:211], v190 offset:17408
	ds_read_b128 v[212:215], v190 offset:18432
	ds_read_b128 v[216:219], v190 offset:19456
	ds_read_b128 v[220:223], v190 offset:20480
	ds_read_b128 v[224:227], v190 offset:21504
	ds_read_b128 v[228:231], v190 offset:22528
	ds_read_b128 v[232:235], v190 offset:23552
	global_load_lds_dwordx4 v[168:169], off
	s_add_i32 m0, vcc_hi, 0x2000
	v_lshl_add_u64 v[236:237], s[72:73], 0, v[130:131]
	s_add_u32 s72, s72, s82
	s_addc_u32 s73, s73, 0
	s_add_i32 s25, s25, s37
	global_load_lds_dwordx4 v[236:237], off
	v_lshl_add_u64 v[238:239], s[72:73], 0, v[0:1]
	s_mov_b32 m0, s25
	v_lshl_add_u64 v[240:241], s[72:73], 0, v[130:131]
	global_load_lds_dwordx4 v[238:239], off
	s_add_i32 m0, s25, 0x2000
	v_lshl_add_u64 v[242:243], s[4:5], 0, v[0:1]
	global_load_lds_dwordx4 v[240:241], off
	s_mov_b32 m0, s71
	v_lshl_add_u64 v[244:245], s[4:5], 0, v[130:131]
	global_load_lds_dwordx4 v[242:243], off
	s_mov_b32 m0, s75
	s_nop 0
	global_load_lds_dwordx4 v[244:245], off
	s_waitcnt vmcnt(8)
	s_waitcnt lgkmcnt(0)
	s_barrier
; #define PG8_STAGE(bufoff, gbase, voff) do { _Pragma("unroll") for (int _i = 0; _i < 2; ++_i) \
;         __builtin_amdgcn_global_load_lds((const unsigned*)((const char*)(gbase) + (voff)[_i]), (LAS unsigned*)(lds + (bufoff) + ldsw + _i * 8192), 16, 0, 0); } while (0)
; #define PG8_LDA(dst, b, h) do { _Pragma("unroll") for (int m = 0; m < 4; ++m) _Pragma("unroll") for (int k = 0; k < 2; ++k) dst[m][k] = *(const LAS bf16x8*)(lds + PG8_SA(b, h) + aoff + m * 2048 + k * 1024); } while (0)
; #define PG8_LDB(dst, b, h) do { _Pragma("unroll") for (int n = 0; n < 2; ++n) _Pragma("unroll") for (int k = 0; k < 2; ++k) dst[n][k] = *(const LAS bf16x8*)(lds + PG8_SB(b, h) + boff + n * 2048 + k * 1024); } while (0)
; #define PG8_MMA(ai, bj, At, Bt) do { __builtin_amdgcn_s_setprio(1); _Pragma("unroll") for (int m = 0; m < 4; ++m) _Pragma("unroll") for (int n = 0; n < 2; ++n) _Pragma("unroll") for (int k = 0; k < 2; ++k) \
;         acc[ai][bj][m][n] = __builtin_amdgcn_mfma_f32_16x16x32_bf16(Bt[n][k], At[m][k], acc[ai][bj][m][n], 0, 0, 0); __builtin_amdgcn_s_setprio(0); } while (0)
; #define PG8_WAIT_V(n) asm volatile("s_waitcnt vmcnt(" #n ")" ::: "memory")
; #define PG8_WAIT_L(n) asm volatile("s_waitcnt lgkmcnt(" #n ")" ::: "memory")
; #define PG8_BAR __builtin_amdgcn_s_barrier()
; #define PG8_SCHED __builtin_amdgcn_sched_barrier(0)
; template <class Epi>
; __device__ __forceinline__ void gemm_phase(LAS unsigned char* lds, const Gemm g, const Epi& E) {
;     ...
;             PG8_WAIT_V(8); PG8_WAIT_L(0); PG8_BAR; PG8_MMA(1, 0, At, B0); PG8_MMA(1, 1, At, B1); PG8_BAR; PG8_SCHED;
;             PG8_LDB(B0, 1, 0); PG8_LDB(B1, 1, 1); PG8_SCHED; PG8_LDA(At, 1, 0); PG8_STAGE(PG8_SA(0, 1), a2 + hstep, voffA);
;             PG8_WAIT_V(8); PG8_WAIT_L(0); PG8_BAR; PG8_MMA(0, 0, At, B0); PG8_MMA(0, 1, At, B1); PG8_BAR; PG8_SCHED;
;             PG8_LDA(At, 1, 1); PG8_STAGE(PG8_SB(1, 0), b3, voffA); PG8_STAGE(PG8_SB(1, 1), b3 + hstep, voffA); PG8_STAGE(PG8_SA(1, 0), a3, voffA);
	s_waitcnt lgkmcnt(0)
	v_mfma_f32_16x16x32_bf16 v[62:65], v[148:151], v[204:207], v[62:65]
	v_mfma_f32_16x16x32_bf16 v[58:61], v[156:159], v[204:207], v[58:61]
	v_mfma_f32_16x16x32_bf16 v[46:49], v[148:151], v[212:215], v[46:49]
	v_mfma_f32_16x16x32_bf16 v[42:45], v[156:159], v[212:215], v[42:45]
	v_mfma_f32_16x16x32_bf16 v[30:33], v[148:151], v[220:223], v[30:33]
	v_mfma_f32_16x16x32_bf16 v[26:29], v[156:159], v[220:223], v[26:29]
	v_mfma_f32_16x16x32_bf16 v[14:17], v[148:151], v[228:231], v[14:17]
	v_mfma_f32_16x16x32_bf16 v[10:13], v[156:159], v[228:231], v[10:13]
	v_mfma_f32_16x16x32_bf16 v[62:65], v[152:155], v[208:211], v[62:65]
	v_mfma_f32_16x16x32_bf16 v[58:61], v[160:163], v[208:211], v[58:61]
	v_mfma_f32_16x16x32_bf16 v[46:49], v[152:155], v[216:219], v[46:49]
	v_mfma_f32_16x16x32_bf16 v[42:45], v[160:163], v[216:219], v[42:45]
	v_mfma_f32_16x16x32_bf16 v[30:33], v[152:155], v[224:227], v[30:33]
	v_mfma_f32_16x16x32_bf16 v[26:29], v[160:163], v[224:227], v[26:29]
	v_mfma_f32_16x16x32_bf16 v[14:17], v[152:155], v[232:235], v[14:17]
	v_mfma_f32_16x16x32_bf16 v[10:13], v[160:163], v[232:235], v[10:13]
	v_mfma_f32_16x16x32_bf16 v[54:57], v[164:167], v[204:207], v[54:57]
	v_mfma_f32_16x16x32_bf16 v[50:53], v[196:199], v[204:207], v[50:53]
	v_mfma_f32_16x16x32_bf16 v[38:41], v[164:167], v[212:215], v[38:41]
	v_mfma_f32_16x16x32_bf16 v[34:37], v[196:199], v[212:215], v[34:37]
	v_mfma_f32_16x16x32_bf16 v[22:25], v[164:167], v[220:223], v[22:25]
	v_mfma_f32_16x16x32_bf16 v[18:21], v[196:199], v[220:223], v[18:21]
	v_mfma_f32_16x16x32_bf16 v[6:9], v[164:167], v[228:231], v[6:9]
	v_mfma_f32_16x16x32_bf16 v[2:5], v[196:199], v[228:231], v[2:5]
	v_mfma_f32_16x16x32_bf16 v[54:57], v[192:195], v[208:211], v[54:57]
	v_mfma_f32_16x16x32_bf16 v[50:53], v[200:203], v[208:211], v[50:53]
	v_mfma_f32_16x16x32_bf16 v[38:41], v[192:195], v[216:219], v[38:41]
	v_mfma_f32_16x16x32_bf16 v[34:37], v[200:203], v[216:219], v[34:37]
	v_mfma_f32_16x16x32_bf16 v[22:25], v[192:195], v[224:227], v[22:25]
	v_mfma_f32_16x16x32_bf16 v[18:21], v[200:203], v[224:227], v[18:21]
	v_mfma_f32_16x16x32_bf16 v[6:9], v[192:195], v[232:235], v[6:9]
	v_mfma_f32_16x16x32_bf16 v[2:5], v[200:203], v[232:235], v[2:5]
	s_barrier
	s_add_i32 s25, 0, 0x18000
	v_add_u32_e32 v133, s25, v189
	s_add_i32 s72, 0, 0x1c000
	ds_read_b128 v[148:151], v133
	ds_read_b128 v[152:155], v133 offset:1024
	ds_read_b128 v[156:159], v133 offset:2048
	ds_read_b128 v[160:163], v133 offset:3072
	v_add_u32_e32 v133, s72, v189
	ds_read_b128 v[164:167], v133
	ds_read_b128 v[192:195], v133 offset:1024
	ds_read_b128 v[196:199], v133 offset:2048
	ds_read_b128 v[200:203], v133 offset:3072
	s_add_u32 s4, s4, s82
	s_addc_u32 s5, s5, 0
	s_mov_b32 m0, s76
	v_lshl_add_u64 v[246:247], s[4:5], 0, v[0:1]
	ds_read_b128 v[204:207], v190 offset:32768
	ds_read_b128 v[208:211], v190 offset:33792
	ds_read_b128 v[212:215], v190 offset:34816
	ds_read_b128 v[216:219], v190 offset:35840
	ds_read_b128 v[220:223], v190 offset:36864
	ds_read_b128 v[224:227], v190 offset:37888
	ds_read_b128 v[228:231], v190 offset:38912
	ds_read_b128 v[232:235], v190 offset:39936
	global_load_lds_dwordx4 v[246:247], off
	v_lshl_add_u64 v[246:247], s[4:5], 0, v[130:131]
	s_mov_b32 m0, s77
	s_nop 0
	global_load_lds_dwordx4 v[246:247], off
	s_waitcnt vmcnt(8)
	s_waitcnt lgkmcnt(0)
	s_barrier
	s_waitcnt lgkmcnt(0)
	v_mfma_f32_16x16x32_bf16 v[126:129], v[148:151], v[204:207], v[126:129]
	v_mfma_f32_16x16x32_bf16 v[122:125], v[156:159], v[204:207], v[122:125]
	v_mfma_f32_16x16x32_bf16 v[110:113], v[148:151], v[212:215], v[110:113]
	v_mfma_f32_16x16x32_bf16 v[106:109], v[156:159], v[212:215], v[106:109]
	v_mfma_f32_16x16x32_bf16 v[94:97], v[148:151], v[220:223], v[94:97]
	v_mfma_f32_16x16x32_bf16 v[90:93], v[156:159], v[220:223], v[90:93]
	v_mfma_f32_16x16x32_bf16 v[78:81], v[148:151], v[228:231], v[78:81]
	v_mfma_f32_16x16x32_bf16 v[74:77], v[156:159], v[228:231], v[74:77]
	v_mfma_f32_16x16x32_bf16 v[126:129], v[152:155], v[208:211], v[126:129]
	v_mfma_f32_16x16x32_bf16 v[122:125], v[160:163], v[208:211], v[122:125]
	v_mfma_f32_16x16x32_bf16 v[110:113], v[152:155], v[216:219], v[110:113]
	v_mfma_f32_16x16x32_bf16 v[106:109], v[160:163], v[216:219], v[106:109]
	v_mfma_f32_16x16x32_bf16 v[94:97], v[152:155], v[224:227], v[94:97]
	v_mfma_f32_16x16x32_bf16 v[90:93], v[160:163], v[224:227], v[90:93]
	v_mfma_f32_16x16x32_bf16 v[78:81], v[152:155], v[232:235], v[78:81]
	v_mfma_f32_16x16x32_bf16 v[74:77], v[160:163], v[232:235], v[74:77]
	v_mfma_f32_16x16x32_bf16 v[118:121], v[164:167], v[204:207], v[118:121]
	v_mfma_f32_16x16x32_bf16 v[114:117], v[196:199], v[204:207], v[114:117]
	v_mfma_f32_16x16x32_bf16 v[102:105], v[164:167], v[212:215], v[102:105]
	v_mfma_f32_16x16x32_bf16 v[98:101], v[196:199], v[212:215], v[98:101]
	v_mfma_f32_16x16x32_bf16 v[86:89], v[164:167], v[220:223], v[86:89]
	v_mfma_f32_16x16x32_bf16 v[82:85], v[196:199], v[220:223], v[82:85]
	v_mfma_f32_16x16x32_bf16 v[70:73], v[164:167], v[228:231], v[70:73]
	v_mfma_f32_16x16x32_bf16 v[66:69], v[196:199], v[228:231], v[66:69]
	v_mfma_f32_16x16x32_bf16 v[118:121], v[192:195], v[208:211], v[118:121]
	v_mfma_f32_16x16x32_bf16 v[114:117], v[200:203], v[208:211], v[114:117]
	v_mfma_f32_16x16x32_bf16 v[102:105], v[192:195], v[216:219], v[102:105]
	v_mfma_f32_16x16x32_bf16 v[98:101], v[200:203], v[216:219], v[98:101]
	v_mfma_f32_16x16x32_bf16 v[86:89], v[192:195], v[224:227], v[86:89]
	v_mfma_f32_16x16x32_bf16 v[82:85], v[200:203], v[224:227], v[82:85]
	v_mfma_f32_16x16x32_bf16 v[70:73], v[192:195], v[232:235], v[70:73]
	v_mfma_f32_16x16x32_bf16 v[66:69], v[200:203], v[232:235], v[66:69]
	s_barrier
; #define PG8_STAGE(bufoff, gbase, voff) do { _Pragma("unroll") for (int _i = 0; _i < 2; ++_i) \
;         __builtin_amdgcn_global_load_lds((const unsigned*)((const char*)(gbase) + (voff)[_i]), (LAS unsigned*)(lds + (bufoff) + ldsw + _i * 8192), 16, 0, 0); } while (0)
; #define PG8_LDA(dst, b, h) do { _Pragma("unroll") for (int m = 0; m < 4; ++m) _Pragma("unroll") for (int k = 0; k < 2; ++k) dst[m][k] = *(const LAS bf16x8*)(lds + PG8_SA(b, h) + aoff + m * 2048 + k * 1024); } while (0)
; #define PG8_MMA(ai, bj, At, Bt) do { __builtin_amdgcn_s_setprio(1); _Pragma("unroll") for (int m = 0; m < 4; ++m) _Pragma("unroll") for (int n = 0; n < 2; ++n) _Pragma("unroll") for (int k = 0; k < 2; ++k) \
;         acc[ai][bj][m][n] = __builtin_amdgcn_mfma_f32_16x16x32_bf16(Bt[n][k], At[m][k], acc[ai][bj][m][n], 0, 0, 0); __builtin_amdgcn_s_setprio(0); } while (0)
; #define PG8_WAIT_V(n) asm volatile("s_waitcnt vmcnt(" #n ")" ::: "memory")
; #define PG8_WAIT_L(n) asm volatile("s_waitcnt lgkmcnt(" #n ")" ::: "memory")
; #define PG8_BAR __builtin_amdgcn_s_barrier()
; #define PG8_SCHED __builtin_amdgcn_sched_barrier(0)
; template <class Epi>
; __device__ __forceinline__ void gemm_phase(LAS unsigned char* lds, const Gemm g, const Epi& E) {
;     ...
;             PG8_LDA(At, 1, 1); PG8_STAGE(PG8_SB(1, 0), b3, voffA); PG8_STAGE(PG8_SB(1, 1), b3 + hstep, voffA); PG8_STAGE(PG8_SA(1, 0), a3, voffA);
;             PG8_WAIT_V(8); PG8_WAIT_L(0); PG8_BAR; PG8_MMA(1, 0, At, B0); PG8_MMA(1, 1, At, B1); PG8_BAR; PG8_SCHED;
	s_add_i32 s4, s25, s37
	v_lshl_add_u64 v[168:169], v[168:169], 0, s[80:81]
	s_mov_b32 m0, s4
	ds_read_b128 v[204:207], v190 offset:49152
	ds_read_b128 v[208:211], v190 offset:50176
	ds_read_b128 v[212:215], v190 offset:51200
	ds_read_b128 v[216:219], v190 offset:52224
	ds_read_b128 v[220:223], v190 offset:53248
	ds_read_b128 v[224:227], v190 offset:54272
	ds_read_b128 v[228:231], v190 offset:55296
	ds_read_b128 v[232:235], v190 offset:56320
	global_load_lds_dwordx4 v[168:169], off
	v_lshl_add_u64 v[168:169], v[236:237], 0, s[80:81]
	s_add_i32 m0, s4, 0x2000
	s_add_i32 s4, s72, s37
	global_load_lds_dwordx4 v[168:169], off
	v_lshl_add_u64 v[168:169], v[238:239], 0, s[80:81]
	s_mov_b32 m0, s4
	s_nop 0
	global_load_lds_dwordx4 v[168:169], off
	v_lshl_add_u64 v[168:169], v[240:241], 0, s[80:81]
	s_add_i32 m0, s4, 0x2000
	s_nop 0
	global_load_lds_dwordx4 v[168:169], off
	v_lshl_add_u64 v[168:169], v[242:243], 0, s[80:81]
	s_mov_b32 m0, s58
	s_nop 0
	global_load_lds_dwordx4 v[168:169], off
	v_lshl_add_u64 v[168:169], v[244:245], 0, s[80:81]
	s_mov_b32 m0, s59
	s_nop 0
	global_load_lds_dwordx4 v[168:169], off
	s_waitcnt vmcnt(8)
	s_waitcnt lgkmcnt(0)
	s_barrier
	s_waitcnt lgkmcnt(0)
	v_mfma_f32_16x16x32_bf16 v[62:65], v[148:151], v[204:207], v[62:65]
	v_mfma_f32_16x16x32_bf16 v[58:61], v[156:159], v[204:207], v[58:61]
	v_mfma_f32_16x16x32_bf16 v[46:49], v[148:151], v[212:215], v[46:49]
	v_mfma_f32_16x16x32_bf16 v[42:45], v[156:159], v[212:215], v[42:45]
	v_mfma_f32_16x16x32_bf16 v[30:33], v[148:151], v[220:223], v[30:33]
	v_mfma_f32_16x16x32_bf16 v[26:29], v[156:159], v[220:223], v[26:29]
	v_mfma_f32_16x16x32_bf16 v[14:17], v[148:151], v[228:231], v[14:17]
	v_mfma_f32_16x16x32_bf16 v[10:13], v[156:159], v[228:231], v[10:13]
	v_mfma_f32_16x16x32_bf16 v[62:65], v[152:155], v[208:211], v[62:65]
	v_mfma_f32_16x16x32_bf16 v[58:61], v[160:163], v[208:211], v[58:61]
	v_mfma_f32_16x16x32_bf16 v[46:49], v[152:155], v[216:219], v[46:49]
	v_mfma_f32_16x16x32_bf16 v[42:45], v[160:163], v[216:219], v[42:45]
	v_mfma_f32_16x16x32_bf16 v[30:33], v[152:155], v[224:227], v[30:33]
	v_mfma_f32_16x16x32_bf16 v[26:29], v[160:163], v[224:227], v[26:29]
	v_mfma_f32_16x16x32_bf16 v[14:17], v[152:155], v[232:235], v[14:17]
	v_mfma_f32_16x16x32_bf16 v[10:13], v[160:163], v[232:235], v[10:13]
	v_mfma_f32_16x16x32_bf16 v[54:57], v[164:167], v[204:207], v[54:57]
	v_mfma_f32_16x16x32_bf16 v[50:53], v[196:199], v[204:207], v[50:53]
	v_mfma_f32_16x16x32_bf16 v[38:41], v[164:167], v[212:215], v[38:41]
	v_mfma_f32_16x16x32_bf16 v[34:37], v[196:199], v[212:215], v[34:37]
	v_mfma_f32_16x16x32_bf16 v[22:25], v[164:167], v[220:223], v[22:25]
	v_mfma_f32_16x16x32_bf16 v[18:21], v[196:199], v[220:223], v[18:21]
	v_mfma_f32_16x16x32_bf16 v[6:9], v[164:167], v[228:231], v[6:9]
	v_mfma_f32_16x16x32_bf16 v[2:5], v[196:199], v[228:231], v[2:5]
	v_mfma_f32_16x16x32_bf16 v[54:57], v[192:195], v[208:211], v[54:57]
	v_mfma_f32_16x16x32_bf16 v[50:53], v[200:203], v[208:211], v[50:53]
	v_mfma_f32_16x16x32_bf16 v[38:41], v[192:195], v[216:219], v[38:41]
	v_mfma_f32_16x16x32_bf16 v[34:37], v[200:203], v[216:219], v[34:37]
	v_mfma_f32_16x16x32_bf16 v[22:25], v[192:195], v[224:227], v[22:25]
	v_mfma_f32_16x16x32_bf16 v[18:21], v[200:203], v[224:227], v[18:21]
	v_mfma_f32_16x16x32_bf16 v[6:9], v[192:195], v[232:235], v[6:9]
	v_mfma_f32_16x16x32_bf16 v[2:5], v[200:203], v[232:235], v[2:5]
	s_barrier
	s_add_u32 s62, s62, 0x100
	s_addc_u32 s63, s63, 0
	s_add_u32 s15, s15, 0x100
	s_addc_u32 s53, s53, 0
	s_cmp_ge_i32 vcc_lo, s70
	s_mov_b32 s4, vcc_lo
	s_cbranch_scc0 .LBB0_407
	s_and_b64 vcc, exec, s[12:13]
	s_cbranch_vccz .LBB0_410

; #define PG8_STAGE(bufoff, gbase, voff) do { _Pragma("unroll") for (int _i = 0; _i < 2; ++_i) \
;         __builtin_amdgcn_global_load_lds((const unsigned*)((const char*)(gbase) + (voff)[_i]), (LAS unsigned*)(lds + (bufoff) + ldsw + _i * 8192), 16, 0, 0); } while (0)
; #define PG8_LDA(dst, b, h) do { _Pragma("unroll") for (int m = 0; m < 4; ++m) _Pragma("unroll") for (int k = 0; k < 2; ++k) dst[m][k] = *(const LAS bf16x8*)(lds + PG8_SA(b, h) + aoff + m * 2048 + k * 1024); } while (0)
; #define PG8_LDB(dst, b, h) do { _Pragma("unroll") for (int n = 0; n < 2; ++n) _Pragma("unroll") for (int k = 0; k < 2; ++k) dst[n][k] = *(const LAS bf16x8*)(lds + PG8_SB(b, h) + boff + n * 2048 + k * 1024); } while (0)
; #define PG8_MMA(ai, bj, At, Bt) do { __builtin_amdgcn_s_setprio(1); _Pragma("unroll") for (int m = 0; m < 4; ++m) _Pragma("unroll") for (int n = 0; n < 2; ++n) _Pragma("unroll") for (int k = 0; k < 2; ++k) \
;         acc[ai][bj][m][n] = __builtin_amdgcn_mfma_f32_16x16x32_bf16(Bt[n][k], At[m][k], acc[ai][bj][m][n], 0, 0, 0); __builtin_amdgcn_s_setprio(0); } while (0)
; #define PG8_WAIT_V(n) asm volatile("s_waitcnt vmcnt(" #n ")" ::: "memory")
; #define PG8_WAIT_L(n) asm volatile("s_waitcnt lgkmcnt(" #n ")" ::: "memory")
; #define PG8_BAR __builtin_amdgcn_s_barrier()
; #define PG8_SCHED __builtin_amdgcn_sched_barrier(0)
; template <class Epi>
; __device__ __forceinline__ void gemm_phase(LAS unsigned char* lds, const Gemm g, const Epi& E) {
;     ...
;             PG8_LDB(B0, 0, 0); PG8_LDB(B1, 0, 1); PG8_SCHED; PG8_LDA(At, 0, 0); PG8_STAGE(PG8_SA(1, 1), a1 + hstep, voffA);
;             PG8_WAIT_V(8); PG8_WAIT_L(0); PG8_BAR; PG8_MMA(0, 0, At, B0); PG8_MMA(0, 1, At, B1); PG8_BAR; PG8_SCHED;
;             PG8_LDA(At, 0, 1); PG8_STAGE(PG8_SB(0, 0), b2, voffA); PG8_STAGE(PG8_SB(0, 1), b2 + hstep, voffA); PG8_STAGE(PG8_SA(0, 0), a2, voffA);
.Lrw3a_d:
	s_waitcnt lgkmcnt(0)
	s_barrier
	s_waitcnt lgkmcnt(0)
	v_mfma_f32_16x16x32_bf16 v[126:129], v[146:149], v[198:201], v[126:129]
	v_mfma_f32_16x16x32_bf16 v[118:121], v[154:157], v[198:201], v[118:121]
	v_mfma_f32_16x16x32_bf16 v[110:113], v[146:149], v[206:209], v[110:113]
	v_mfma_f32_16x16x32_bf16 v[102:105], v[154:157], v[206:209], v[102:105]
	v_mfma_f32_16x16x32_bf16 v[94:97], v[146:149], v[214:217], v[94:97]
	v_mfma_f32_16x16x32_bf16 v[86:89], v[154:157], v[214:217], v[86:89]
	v_mfma_f32_16x16x32_bf16 v[78:81], v[146:149], v[222:225], v[78:81]
	v_mfma_f32_16x16x32_bf16 v[70:73], v[154:157], v[222:225], v[70:73]
	v_mfma_f32_16x16x32_bf16 v[126:129], v[150:153], v[202:205], v[126:129]
	v_mfma_f32_16x16x32_bf16 v[118:121], v[158:161], v[202:205], v[118:121]
	v_mfma_f32_16x16x32_bf16 v[110:113], v[150:153], v[210:213], v[110:113]
	v_mfma_f32_16x16x32_bf16 v[102:105], v[158:161], v[210:213], v[102:105]
	v_mfma_f32_16x16x32_bf16 v[94:97], v[150:153], v[218:221], v[94:97]
	v_mfma_f32_16x16x32_bf16 v[86:89], v[158:161], v[218:221], v[86:89]
	v_mfma_f32_16x16x32_bf16 v[78:81], v[150:153], v[226:229], v[78:81]
	v_mfma_f32_16x16x32_bf16 v[70:73], v[158:161], v[226:229], v[70:73]
	v_mfma_f32_16x16x32_bf16 v[122:125], v[162:165], v[198:201], v[122:125]
	v_mfma_f32_16x16x32_bf16 v[114:117], v[190:193], v[198:201], v[114:117]
	v_mfma_f32_16x16x32_bf16 v[106:109], v[162:165], v[206:209], v[106:109]
	v_mfma_f32_16x16x32_bf16 v[98:101], v[190:193], v[206:209], v[98:101]
	v_mfma_f32_16x16x32_bf16 v[90:93], v[162:165], v[214:217], v[90:93]
	v_mfma_f32_16x16x32_bf16 v[82:85], v[190:193], v[214:217], v[82:85]
	v_mfma_f32_16x16x32_bf16 v[74:77], v[162:165], v[222:225], v[74:77]
	v_mfma_f32_16x16x32_bf16 v[66:69], v[190:193], v[222:225], v[66:69]
	v_mfma_f32_16x16x32_bf16 v[122:125], v[166:169], v[202:205], v[122:125]
	v_mfma_f32_16x16x32_bf16 v[114:117], v[194:197], v[202:205], v[114:117]
	v_mfma_f32_16x16x32_bf16 v[106:109], v[166:169], v[210:213], v[106:109]
	v_mfma_f32_16x16x32_bf16 v[98:101], v[194:197], v[210:213], v[98:101]
	v_mfma_f32_16x16x32_bf16 v[90:93], v[166:169], v[218:221], v[90:93]
	v_mfma_f32_16x16x32_bf16 v[82:85], v[194:197], v[218:221], v[82:85]
	v_mfma_f32_16x16x32_bf16 v[74:77], v[166:169], v[226:229], v[74:77]
	v_mfma_f32_16x16x32_bf16 v[66:69], v[194:197], v[226:229], v[66:69]
	s_barrier
	s_add_i32 s72, s21, s2
	v_lshl_add_u64 v[136:137], s[4:5], 0, v[0:1]
	s_mov_b32 m0, s72
	ds_read_b128 v[198:201], v145 offset:16384
	ds_read_b128 v[202:205], v145 offset:17408
	ds_read_b128 v[206:209], v145 offset:18432
	ds_read_b128 v[210:213], v145 offset:19456
	ds_read_b128 v[214:217], v145 offset:20480
	ds_read_b128 v[218:221], v145 offset:21504
	ds_read_b128 v[222:225], v145 offset:22528
	ds_read_b128 v[226:229], v145 offset:23552
	global_load_lds_dwordx4 v[136:137], off
	s_add_i32 m0, s72, 0x2000
	s_add_u32 s72, s4, 0x40000
	v_lshl_add_u64 v[230:231], s[4:5], 0, v[130:131]
	s_addc_u32 s73, s5, 0
	s_add_i32 s25, s25, s2
	global_load_lds_dwordx4 v[230:231], off
	v_lshl_add_u64 v[232:233], s[72:73], 0, v[0:1]
	s_mov_b32 m0, s25
	v_lshl_add_u64 v[234:235], s[70:71], 0, v[130:131]
	global_load_lds_dwordx4 v[232:233], off
	v_lshl_add_u64 v[232:233], s[72:73], 0, v[130:131]
	s_add_i32 m0, s25, 0x2000
	s_nop 0
	global_load_lds_dwordx4 v[232:233], off
	v_lshl_add_u64 v[232:233], s[70:71], 0, v[0:1]
	s_mov_b32 m0, s7
	s_nop 0
	global_load_lds_dwordx4 v[232:233], off
	s_mov_b32 m0, s9
	s_nop 0
	global_load_lds_dwordx4 v[234:235], off
	s_cmp_eq_u32 s32, 1
	s_cbranch_scc1 .Lrw3b_1
	s_waitcnt vmcnt(16)
	s_branch .Lrw3b_d

; #define PG8_STAGE(bufoff, gbase, voff) do { _Pragma("unroll") for (int _i = 0; _i < 2; ++_i) \
;         __builtin_amdgcn_global_load_lds((const unsigned*)((const char*)(gbase) + (voff)[_i]), (LAS unsigned*)(lds + (bufoff) + ldsw + _i * 8192), 16, 0, 0); } while (0)
; #define PG8_LDA(dst, b, h) do { _Pragma("unroll") for (int m = 0; m < 4; ++m) _Pragma("unroll") for (int k = 0; k < 2; ++k) dst[m][k] = *(const LAS bf16x8*)(lds + PG8_SA(b, h) + aoff + m * 2048 + k * 1024); } while (0)
; #define PG8_LDB(dst, b, h) do { _Pragma("unroll") for (int n = 0; n < 2; ++n) _Pragma("unroll") for (int k = 0; k < 2; ++k) dst[n][k] = *(const LAS bf16x8*)(lds + PG8_SB(b, h) + boff + n * 2048 + k * 1024); } while (0)
; #define PG8_MMA(ai, bj, At, Bt) do { __builtin_amdgcn_s_setprio(1); _Pragma("unroll") for (int m = 0; m < 4; ++m) _Pragma("unroll") for (int n = 0; n < 2; ++n) _Pragma("unroll") for (int k = 0; k < 2; ++k) \
;         acc[ai][bj][m][n] = __builtin_amdgcn_mfma_f32_16x16x32_bf16(Bt[n][k], At[m][k], acc[ai][bj][m][n], 0, 0, 0); __builtin_amdgcn_s_setprio(0); } while (0)
; #define PG8_WAIT_V(n) asm volatile("s_waitcnt vmcnt(" #n ")" ::: "memory")
; #define PG8_WAIT_L(n) asm volatile("s_waitcnt lgkmcnt(" #n ")" ::: "memory")
; #define PG8_BAR __builtin_amdgcn_s_barrier()
; #define PG8_SCHED __builtin_amdgcn_sched_barrier(0)
; template <class Epi>
; __device__ __forceinline__ void gemm_phase(LAS unsigned char* lds, const Gemm g, const Epi& E) {
;     ...
;             PG8_WAIT_V(8); PG8_WAIT_L(0); PG8_BAR; PG8_MMA(1, 0, At, B0); PG8_MMA(1, 1, At, B1); PG8_BAR; PG8_SCHED;
;             PG8_LDB(B0, 1, 0); PG8_LDB(B1, 1, 1); PG8_SCHED; PG8_LDA(At, 1, 0); PG8_STAGE(PG8_SA(0, 1), a2 + hstep, voffA);
;             PG8_WAIT_V(8); PG8_WAIT_L(0); PG8_BAR; PG8_MMA(0, 0, At, B0); PG8_MMA(0, 1, At, B1); PG8_BAR; PG8_SCHED;
;             PG8_LDA(At, 1, 1); PG8_STAGE(PG8_SB(1, 0), b3, voffA); PG8_STAGE(PG8_SB(1, 1), b3 + hstep, voffA); PG8_STAGE(PG8_SA(1, 0), a3, voffA);
.Lrw3b_d:
	s_mov_b32 s32, 0
	s_waitcnt lgkmcnt(0)
	s_barrier
	s_waitcnt lgkmcnt(0)
	v_mfma_f32_16x16x32_bf16 v[62:65], v[146:149], v[198:201], v[62:65]
	v_mfma_f32_16x16x32_bf16 v[54:57], v[154:157], v[198:201], v[54:57]
	v_mfma_f32_16x16x32_bf16 v[46:49], v[146:149], v[206:209], v[46:49]
	v_mfma_f32_16x16x32_bf16 v[38:41], v[154:157], v[206:209], v[38:41]
	v_mfma_f32_16x16x32_bf16 v[30:33], v[146:149], v[214:217], v[30:33]
	v_mfma_f32_16x16x32_bf16 v[22:25], v[154:157], v[214:217], v[22:25]
	v_mfma_f32_16x16x32_bf16 v[14:17], v[146:149], v[222:225], v[14:17]
	v_mfma_f32_16x16x32_bf16 v[6:9], v[154:157], v[222:225], v[6:9]
	v_mfma_f32_16x16x32_bf16 v[62:65], v[150:153], v[202:205], v[62:65]
	v_mfma_f32_16x16x32_bf16 v[54:57], v[158:161], v[202:205], v[54:57]
	v_mfma_f32_16x16x32_bf16 v[46:49], v[150:153], v[210:213], v[46:49]
	v_mfma_f32_16x16x32_bf16 v[38:41], v[158:161], v[210:213], v[38:41]
	v_mfma_f32_16x16x32_bf16 v[30:33], v[150:153], v[218:221], v[30:33]
	v_mfma_f32_16x16x32_bf16 v[22:25], v[158:161], v[218:221], v[22:25]
	v_mfma_f32_16x16x32_bf16 v[14:17], v[150:153], v[226:229], v[14:17]
	v_mfma_f32_16x16x32_bf16 v[6:9], v[158:161], v[226:229], v[6:9]
	v_mfma_f32_16x16x32_bf16 v[58:61], v[162:165], v[198:201], v[58:61]
	v_mfma_f32_16x16x32_bf16 v[50:53], v[190:193], v[198:201], v[50:53]
	v_mfma_f32_16x16x32_bf16 v[42:45], v[162:165], v[206:209], v[42:45]
	v_mfma_f32_16x16x32_bf16 v[34:37], v[190:193], v[206:209], v[34:37]
	v_mfma_f32_16x16x32_bf16 v[26:29], v[162:165], v[214:217], v[26:29]
	v_mfma_f32_16x16x32_bf16 v[18:21], v[190:193], v[214:217], v[18:21]
	v_mfma_f32_16x16x32_bf16 v[10:13], v[162:165], v[222:225], v[10:13]
	v_mfma_f32_16x16x32_bf16 v[2:5], v[190:193], v[222:225], v[2:5]
	v_mfma_f32_16x16x32_bf16 v[58:61], v[166:169], v[202:205], v[58:61]
	v_mfma_f32_16x16x32_bf16 v[50:53], v[194:197], v[202:205], v[50:53]
	v_mfma_f32_16x16x32_bf16 v[42:45], v[166:169], v[210:213], v[42:45]
	v_mfma_f32_16x16x32_bf16 v[34:37], v[194:197], v[210:213], v[34:37]
	v_mfma_f32_16x16x32_bf16 v[26:29], v[166:169], v[218:221], v[26:29]
	v_mfma_f32_16x16x32_bf16 v[18:21], v[194:197], v[218:221], v[18:21]
	v_mfma_f32_16x16x32_bf16 v[10:13], v[166:169], v[226:229], v[10:13]
	v_mfma_f32_16x16x32_bf16 v[2:5], v[194:197], v[226:229], v[2:5]
	s_barrier
	s_add_i32 s25, 0, 0x18000
	s_add_i32 s72, 0, 0x1c000
	v_add_u32_e32 v158, s25, v144
	v_add_u32_e32 v189, s72, v144
	ds_read_b128 v[146:149], v158
	ds_read_b128 v[150:153], v158 offset:1024
	ds_read_b128 v[154:157], v158 offset:2048
	ds_read_b128 v[158:161], v158 offset:3072
	ds_read_b128 v[162:165], v189
	ds_read_b128 v[166:169], v189 offset:1024
	ds_read_b128 v[190:193], v189 offset:2048
	ds_read_b128 v[194:197], v189 offset:3072
	s_add_u32 s70, s70, 0x40000
	s_addc_u32 s71, s71, 0
	s_mov_b32 m0, s45
	v_lshl_add_u64 v[236:237], s[70:71], 0, v[0:1]
	ds_read_b128 v[198:201], v145 offset:32768
	ds_read_b128 v[202:205], v145 offset:33792
	ds_read_b128 v[206:209], v145 offset:34816
	ds_read_b128 v[210:213], v145 offset:35840
	ds_read_b128 v[214:217], v145 offset:36864
	ds_read_b128 v[218:221], v145 offset:37888
	ds_read_b128 v[222:225], v145 offset:38912
	ds_read_b128 v[226:229], v145 offset:39936
	global_load_lds_dwordx4 v[236:237], off
	v_lshl_add_u64 v[236:237], s[70:71], 0, v[130:131]
	s_mov_b32 m0, s52
	s_nop 0
	global_load_lds_dwordx4 v[236:237], off
	s_waitcnt vmcnt(8)
	s_waitcnt lgkmcnt(0)
	s_barrier
	s_waitcnt lgkmcnt(0)
	v_mfma_f32_16x16x32_bf16 v[126:129], v[146:149], v[198:201], v[126:129]
	v_mfma_f32_16x16x32_bf16 v[118:121], v[154:157], v[198:201], v[118:121]
	v_mfma_f32_16x16x32_bf16 v[110:113], v[146:149], v[206:209], v[110:113]
	v_mfma_f32_16x16x32_bf16 v[102:105], v[154:157], v[206:209], v[102:105]
	v_mfma_f32_16x16x32_bf16 v[94:97], v[146:149], v[214:217], v[94:97]
	v_mfma_f32_16x16x32_bf16 v[86:89], v[154:157], v[214:217], v[86:89]
	v_mfma_f32_16x16x32_bf16 v[78:81], v[146:149], v[222:225], v[78:81]
	v_mfma_f32_16x16x32_bf16 v[70:73], v[154:157], v[222:225], v[70:73]
	v_mfma_f32_16x16x32_bf16 v[126:129], v[150:153], v[202:205], v[126:129]
	v_mfma_f32_16x16x32_bf16 v[118:121], v[158:161], v[202:205], v[118:121]
	v_mfma_f32_16x16x32_bf16 v[110:113], v[150:153], v[210:213], v[110:113]
	v_mfma_f32_16x16x32_bf16 v[102:105], v[158:161], v[210:213], v[102:105]
	v_mfma_f32_16x16x32_bf16 v[94:97], v[150:153], v[218:221], v[94:97]
	v_mfma_f32_16x16x32_bf16 v[86:89], v[158:161], v[218:221], v[86:89]
	v_mfma_f32_16x16x32_bf16 v[78:81], v[150:153], v[226:229], v[78:81]
	v_mfma_f32_16x16x32_bf16 v[70:73], v[158:161], v[226:229], v[70:73]
	v_mfma_f32_16x16x32_bf16 v[122:125], v[162:165], v[198:201], v[122:125]
	v_mfma_f32_16x16x32_bf16 v[114:117], v[190:193], v[198:201], v[114:117]
	v_mfma_f32_16x16x32_bf16 v[106:109], v[162:165], v[206:209], v[106:109]
	v_mfma_f32_16x16x32_bf16 v[98:101], v[190:193], v[206:209], v[98:101]
	v_mfma_f32_16x16x32_bf16 v[90:93], v[162:165], v[214:217], v[90:93]
	v_mfma_f32_16x16x32_bf16 v[82:85], v[190:193], v[214:217], v[82:85]
	v_mfma_f32_16x16x32_bf16 v[74:77], v[162:165], v[222:225], v[74:77]
	v_mfma_f32_16x16x32_bf16 v[66:69], v[190:193], v[222:225], v[66:69]
	v_mfma_f32_16x16x32_bf16 v[122:125], v[166:169], v[202:205], v[122:125]
	v_mfma_f32_16x16x32_bf16 v[114:117], v[194:197], v[202:205], v[114:117]
	v_mfma_f32_16x16x32_bf16 v[106:109], v[166:169], v[210:213], v[106:109]
	v_mfma_f32_16x16x32_bf16 v[98:101], v[194:197], v[210:213], v[98:101]
	v_mfma_f32_16x16x32_bf16 v[90:93], v[166:169], v[218:221], v[90:93]
	v_mfma_f32_16x16x32_bf16 v[82:85], v[194:197], v[218:221], v[82:85]
	v_mfma_f32_16x16x32_bf16 v[74:77], v[166:169], v[226:229], v[74:77]
	v_mfma_f32_16x16x32_bf16 v[66:69], v[194:197], v[226:229], v[66:69]
	s_barrier
; #define PG8_STAGE(bufoff, gbase, voff) do { _Pragma("unroll") for (int _i = 0; _i < 2; ++_i) \
;         __builtin_amdgcn_global_load_lds((const unsigned*)((const char*)(gbase) + (voff)[_i]), (LAS unsigned*)(lds + (bufoff) + ldsw + _i * 8192), 16, 0, 0); } while (0)
; #define PG8_LDA(dst, b, h) do { _Pragma("unroll") for (int m = 0; m < 4; ++m) _Pragma("unroll") for (int k = 0; k < 2; ++k) dst[m][k] = *(const LAS bf16x8*)(lds + PG8_SA(b, h) + aoff + m * 2048 + k * 1024); } while (0)
; #define PG8_MMA(ai, bj, At, Bt) do { __builtin_amdgcn_s_setprio(1); _Pragma("unroll") for (int m = 0; m < 4; ++m) _Pragma("unroll") for (int n = 0; n < 2; ++n) _Pragma("unroll") for (int k = 0; k < 2; ++k) \
;         acc[ai][bj][m][n] = __builtin_amdgcn_mfma_f32_16x16x32_bf16(Bt[n][k], At[m][k], acc[ai][bj][m][n], 0, 0, 0); __builtin_amdgcn_s_setprio(0); } while (0)
; #define PG8_WAIT_V(n) asm volatile("s_waitcnt vmcnt(" #n ")" ::: "memory")
; #define PG8_WAIT_L(n) asm volatile("s_waitcnt lgkmcnt(" #n ")" ::: "memory")
; #define PG8_BAR __builtin_amdgcn_s_barrier()
; #define PG8_SCHED __builtin_amdgcn_sched_barrier(0)
; template <class Epi>
; __device__ __forceinline__ void gemm_phase(LAS unsigned char* lds, const Gemm g, const Epi& E) {
;     ...
;             PG8_LDA(At, 1, 1); PG8_STAGE(PG8_SB(1, 0), b3, voffA); PG8_STAGE(PG8_SB(1, 1), b3 + hstep, voffA); PG8_STAGE(PG8_SA(1, 0), a3, voffA);
;             PG8_WAIT_V(8); PG8_WAIT_L(0); PG8_BAR; PG8_MMA(1, 0, At, B0); PG8_MMA(1, 1, At, B1); PG8_BAR; PG8_SCHED;
	s_add_i32 s25, s25, s2
	v_lshl_add_u64 v[136:137], v[136:137], 0, s[80:81]
	s_mov_b32 m0, s25
	ds_read_b128 v[198:201], v145 offset:49152
	ds_read_b128 v[202:205], v145 offset:50176
	ds_read_b128 v[206:209], v145 offset:51200
	ds_read_b128 v[210:213], v145 offset:52224
	ds_read_b128 v[214:217], v145 offset:53248
	ds_read_b128 v[218:221], v145 offset:54272
	ds_read_b128 v[222:225], v145 offset:55296
	ds_read_b128 v[226:229], v145 offset:56320
	global_load_lds_dwordx4 v[136:137], off
	s_add_i32 m0, s25, 0x2000
	s_add_u32 s4, s4, 0x40080
	v_lshl_add_u64 v[136:137], v[230:231], 0, s[80:81]
	s_addc_u32 s5, s5, 0
	s_add_i32 s25, s72, s2
	global_load_lds_dwordx4 v[136:137], off
	v_lshl_add_u64 v[136:137], s[4:5], 0, v[0:1]
	s_mov_b32 m0, s25
	s_nop 0
	global_load_lds_dwordx4 v[136:137], off
	v_lshl_add_u64 v[136:137], s[4:5], 0, v[130:131]
	s_add_i32 m0, s25, 0x2000
	s_nop 0
	global_load_lds_dwordx4 v[136:137], off
	v_lshl_add_u64 v[136:137], v[232:233], 0, s[80:81]
	s_mov_b32 m0, s75
	s_nop 0
	global_load_lds_dwordx4 v[136:137], off
	v_lshl_add_u64 v[136:137], v[234:235], 0, s[80:81]
	s_mov_b32 m0, s76
	s_nop 0
	global_load_lds_dwordx4 v[136:137], off
	s_waitcnt vmcnt(8)
	s_waitcnt lgkmcnt(0)
	s_barrier
	s_waitcnt lgkmcnt(0)
	v_mfma_f32_16x16x32_bf16 v[62:65], v[146:149], v[198:201], v[62:65]
	v_mfma_f32_16x16x32_bf16 v[54:57], v[154:157], v[198:201], v[54:57]
	v_mfma_f32_16x16x32_bf16 v[46:49], v[146:149], v[206:209], v[46:49]
	v_mfma_f32_16x16x32_bf16 v[38:41], v[154:157], v[206:209], v[38:41]
	v_mfma_f32_16x16x32_bf16 v[30:33], v[146:149], v[214:217], v[30:33]
	v_mfma_f32_16x16x32_bf16 v[22:25], v[154:157], v[214:217], v[22:25]
	v_mfma_f32_16x16x32_bf16 v[14:17], v[146:149], v[222:225], v[14:17]
	v_mfma_f32_16x16x32_bf16 v[6:9], v[154:157], v[222:225], v[6:9]
	v_mfma_f32_16x16x32_bf16 v[62:65], v[150:153], v[202:205], v[62:65]
	v_mfma_f32_16x16x32_bf16 v[54:57], v[158:161], v[202:205], v[54:57]
	v_mfma_f32_16x16x32_bf16 v[46:49], v[150:153], v[210:213], v[46:49]
	v_mfma_f32_16x16x32_bf16 v[38:41], v[158:161], v[210:213], v[38:41]
	v_mfma_f32_16x16x32_bf16 v[30:33], v[150:153], v[218:221], v[30:33]
	v_mfma_f32_16x16x32_bf16 v[22:25], v[158:161], v[218:221], v[22:25]
	v_mfma_f32_16x16x32_bf16 v[14:17], v[150:153], v[226:229], v[14:17]
	v_mfma_f32_16x16x32_bf16 v[6:9], v[158:161], v[226:229], v[6:9]
	v_mfma_f32_16x16x32_bf16 v[58:61], v[162:165], v[198:201], v[58:61]
	v_mfma_f32_16x16x32_bf16 v[50:53], v[190:193], v[198:201], v[50:53]
	v_mfma_f32_16x16x32_bf16 v[42:45], v[162:165], v[206:209], v[42:45]
	v_mfma_f32_16x16x32_bf16 v[34:37], v[190:193], v[206:209], v[34:37]
	v_mfma_f32_16x16x32_bf16 v[26:29], v[162:165], v[214:217], v[26:29]
	v_mfma_f32_16x16x32_bf16 v[18:21], v[190:193], v[214:217], v[18:21]
	v_mfma_f32_16x16x32_bf16 v[10:13], v[162:165], v[222:225], v[10:13]
	v_mfma_f32_16x16x32_bf16 v[2:5], v[190:193], v[222:225], v[2:5]
	v_mfma_f32_16x16x32_bf16 v[58:61], v[166:169], v[202:205], v[58:61]
	v_mfma_f32_16x16x32_bf16 v[50:53], v[194:197], v[202:205], v[50:53]
	v_mfma_f32_16x16x32_bf16 v[42:45], v[166:169], v[210:213], v[42:45]
	v_mfma_f32_16x16x32_bf16 v[34:37], v[194:197], v[210:213], v[34:37]
	v_mfma_f32_16x16x32_bf16 v[26:29], v[166:169], v[218:221], v[26:29]
	v_mfma_f32_16x16x32_bf16 v[18:21], v[194:197], v[218:221], v[18:21]
	v_mfma_f32_16x16x32_bf16 v[10:13], v[166:169], v[226:229], v[10:13]
	v_mfma_f32_16x16x32_bf16 v[2:5], v[194:197], v[226:229], v[2:5]
	s_barrier
	s_add_u32 s68, s68, 0x100
	s_addc_u32 s69, s69, 0
	s_add_u32 s93, s93, 0x100
	s_addc_u32 vcc_lo, vcc_lo, 0
	s_cmp_ge_i32 vcc_hi, s37
	s_mov_b32 s4, vcc_hi
	s_cbranch_scc0 .LBB0_441
	s_branch .Lk3_exit

; #define PG8_STAGE(bufoff, gbase, voff) do { _Pragma("unroll") for (int _i = 0; _i < 2; ++_i) \
;         __builtin_amdgcn_global_load_lds((const unsigned*)((const char*)(gbase) + (voff)[_i]), (LAS unsigned*)(lds + (bufoff) + ldsw + _i * 8192), 16, 0, 0); } while (0)
; #define PG8_LDA(dst, b, h) do { _Pragma("unroll") for (int m = 0; m < 4; ++m) _Pragma("unroll") for (int k = 0; k < 2; ++k) dst[m][k] = *(const LAS bf16x8*)(lds + PG8_SA(b, h) + aoff + m * 2048 + k * 1024); } while (0)
; #define PG8_LDB(dst, b, h) do { _Pragma("unroll") for (int n = 0; n < 2; ++n) _Pragma("unroll") for (int k = 0; k < 2; ++k) dst[n][k] = *(const LAS bf16x8*)(lds + PG8_SB(b, h) + boff + n * 2048 + k * 1024); } while (0)
; #define PG8_MMA(ai, bj, At, Bt) do { __builtin_amdgcn_s_setprio(1); _Pragma("unroll") for (int m = 0; m < 4; ++m) _Pragma("unroll") for (int n = 0; n < 2; ++n) _Pragma("unroll") for (int k = 0; k < 2; ++k) \
;         acc[ai][bj][m][n] = __builtin_amdgcn_mfma_f32_16x16x32_bf16(Bt[n][k], At[m][k], acc[ai][bj][m][n], 0, 0, 0); __builtin_amdgcn_s_setprio(0); } while (0)
; #define PG8_WAIT_V(n) asm volatile("s_waitcnt vmcnt(" #n ")" ::: "memory")
; #define PG8_WAIT_L(n) asm volatile("s_waitcnt lgkmcnt(" #n ")" ::: "memory")
; #define PG8_BAR __builtin_amdgcn_s_barrier()
; #define PG8_SCHED __builtin_amdgcn_sched_barrier(0)
; template <class Epi>
; __device__ __forceinline__ void gemm_phase(LAS unsigned char* lds, const Gemm g, const Epi& E) {
;     ...
;         for (int t = 0; t < nt; t += 2) {
;             const bool last = (t == nt - 2);
;             const char* a1 = cA + (size_t)(t + 1) * kstep;
;             const char* a2 = last ? nA : cA + (size_t)(t + 2) * kstep; const char* b2 = last ? nB : cB + (size_t)(t + 2) * kstep;
;             const char* a3 = a2 + kstep; const char* b3 = b2 + kstep;
;             PG8_LDB(B0, 0, 0); PG8_LDB(B1, 0, 1); PG8_SCHED; PG8_LDA(At, 0, 0); PG8_STAGE(PG8_SA(1, 1), a1 + hstep, voffA);
;             PG8_WAIT_V(8); PG8_WAIT_L(0); PG8_BAR; PG8_MMA(0, 0, At, B0); PG8_MMA(0, 1, At, B1); PG8_BAR; PG8_SCHED;
;             PG8_LDA(At, 0, 1); PG8_STAGE(PG8_SB(0, 0), b2, voffA); PG8_STAGE(PG8_SB(0, 1), b2 + hstep, voffA); PG8_STAGE(PG8_SA(0, 0), a2, voffA);
;             PG8_WAIT_V(8); PG8_WAIT_L(0); PG8_BAR; PG8_MMA(1, 0, At, B0); PG8_MMA(1, 1, At, B1); PG8_BAR; PG8_SCHED;
.LBB0_441:
	s_add_i32 vcc_hi, s4, 2
	s_add_u32 s5, s68, 0xfffc0080
	s_addc_u32 s70, s69, -1
	s_cmp_eq_u32 s92, s4
	s_cselect_b32 s71, s15, s70
	s_cselect_b32 s70, s55, s5
	v_add_u32_e32 v136, s21, v144
	s_cselect_b32 s5, s57, vcc_lo
	s_cselect_b32 s4, s82, s93
	s_add_i32 s25, 0, 0x14000
	ds_read_b128 v[146:149], v136
	ds_read_b128 v[150:153], v136 offset:1024
	ds_read_b128 v[154:157], v136 offset:2048
	ds_read_b128 v[158:161], v136 offset:3072
	v_add_u32_e32 v136, s25, v144
	ds_read_b128 v[162:165], v136
	ds_read_b128 v[166:169], v136 offset:1024
	ds_read_b128 v[190:193], v136 offset:2048
	ds_read_b128 v[194:197], v136 offset:3072
	v_lshl_add_u64 v[136:137], s[68:69], 0, v[132:133]
	s_add_i32 m0, s7, 0xc000
	ds_read_b128 v[198:201], v145
	ds_read_b128 v[202:205], v145 offset:1024
	ds_read_b128 v[206:209], v145 offset:2048
	ds_read_b128 v[210:213], v145 offset:3072
	ds_read_b128 v[214:217], v145 offset:4096
	ds_read_b128 v[218:221], v145 offset:5120
	ds_read_b128 v[222:225], v145 offset:6144
	ds_read_b128 v[226:229], v145 offset:7168
	global_load_lds_dwordx4 v[136:137], off
	v_lshl_add_u64 v[136:137], s[68:69], 0, v[134:135]
	s_add_i32 m0, s7, 0xe000
	s_nop 0
	global_load_lds_dwordx4 v[136:137], off
	s_waitcnt vmcnt(8)
	s_waitcnt lgkmcnt(0)
	s_barrier
	s_waitcnt lgkmcnt(0)
	v_mfma_f32_16x16x32_bf16 v[126:129], v[146:149], v[198:201], v[126:129]
	v_mfma_f32_16x16x32_bf16 v[118:121], v[154:157], v[198:201], v[118:121]
	v_mfma_f32_16x16x32_bf16 v[110:113], v[146:149], v[206:209], v[110:113]
	v_mfma_f32_16x16x32_bf16 v[102:105], v[154:157], v[206:209], v[102:105]
	v_mfma_f32_16x16x32_bf16 v[94:97], v[146:149], v[214:217], v[94:97]
	v_mfma_f32_16x16x32_bf16 v[86:89], v[154:157], v[214:217], v[86:89]
	v_mfma_f32_16x16x32_bf16 v[78:81], v[146:149], v[222:225], v[78:81]
	v_mfma_f32_16x16x32_bf16 v[70:73], v[154:157], v[222:225], v[70:73]
	v_mfma_f32_16x16x32_bf16 v[126:129], v[150:153], v[202:205], v[126:129]
	v_mfma_f32_16x16x32_bf16 v[118:121], v[158:161], v[202:205], v[118:121]
	v_mfma_f32_16x16x32_bf16 v[110:113], v[150:153], v[210:213], v[110:113]
	v_mfma_f32_16x16x32_bf16 v[102:105], v[158:161], v[210:213], v[102:105]
	v_mfma_f32_16x16x32_bf16 v[94:97], v[150:153], v[218:221], v[94:97]
	v_mfma_f32_16x16x32_bf16 v[86:89], v[158:161], v[218:221], v[86:89]
	v_mfma_f32_16x16x32_bf16 v[78:81], v[150:153], v[226:229], v[78:81]
	v_mfma_f32_16x16x32_bf16 v[70:73], v[158:161], v[226:229], v[70:73]
	v_mfma_f32_16x16x32_bf16 v[122:125], v[162:165], v[198:201], v[122:125]
	v_mfma_f32_16x16x32_bf16 v[114:117], v[190:193], v[198:201], v[114:117]
	v_mfma_f32_16x16x32_bf16 v[106:109], v[162:165], v[206:209], v[106:109]
	v_mfma_f32_16x16x32_bf16 v[98:101], v[190:193], v[206:209], v[98:101]
	v_mfma_f32_16x16x32_bf16 v[90:93], v[162:165], v[214:217], v[90:93]
	v_mfma_f32_16x16x32_bf16 v[82:85], v[190:193], v[214:217], v[82:85]
	v_mfma_f32_16x16x32_bf16 v[74:77], v[162:165], v[222:225], v[74:77]
	v_mfma_f32_16x16x32_bf16 v[66:69], v[190:193], v[222:225], v[66:69]
	v_mfma_f32_16x16x32_bf16 v[122:125], v[166:169], v[202:205], v[122:125]
	v_mfma_f32_16x16x32_bf16 v[114:117], v[194:197], v[202:205], v[114:117]
	v_mfma_f32_16x16x32_bf16 v[106:109], v[166:169], v[210:213], v[106:109]
	v_mfma_f32_16x16x32_bf16 v[98:101], v[194:197], v[210:213], v[98:101]
	v_mfma_f32_16x16x32_bf16 v[90:93], v[166:169], v[218:221], v[90:93]
	v_mfma_f32_16x16x32_bf16 v[82:85], v[194:197], v[218:221], v[82:85]
	v_mfma_f32_16x16x32_bf16 v[74:77], v[166:169], v[226:229], v[74:77]
	v_mfma_f32_16x16x32_bf16 v[66:69], v[194:197], v[226:229], v[66:69]
	s_barrier
	s_add_i32 s72, s21, s2
	v_lshl_add_u64 v[136:137], s[4:5], 0, v[0:1]
	s_mov_b32 m0, s72
	ds_read_b128 v[198:201], v145 offset:16384
	ds_read_b128 v[202:205], v145 offset:17408
	ds_read_b128 v[206:209], v145 offset:18432
	ds_read_b128 v[210:213], v145 offset:19456
	ds_read_b128 v[214:217], v145 offset:20480
	ds_read_b128 v[218:221], v145 offset:21504
	ds_read_b128 v[222:225], v145 offset:22528
	ds_read_b128 v[226:229], v145 offset:23552
	global_load_lds_dwordx4 v[136:137], off
	s_add_i32 m0, s72, 0x2000
	s_add_u32 s72, s4, 0x40000
	v_lshl_add_u64 v[230:231], s[4:5], 0, v[130:131]
	s_addc_u32 s73, s5, 0
	s_add_i32 s25, s25, s2
	global_load_lds_dwordx4 v[230:231], off
	v_lshl_add_u64 v[232:233], s[72:73], 0, v[0:1]
	s_mov_b32 m0, s25
	v_lshl_add_u64 v[234:235], s[70:71], 0, v[130:131]
	global_load_lds_dwordx4 v[232:233], off
	v_lshl_add_u64 v[232:233], s[72:73], 0, v[130:131]
	s_add_i32 m0, s25, 0x2000
	s_nop 0
	global_load_lds_dwordx4 v[232:233], off
	v_lshl_add_u64 v[232:233], s[70:71], 0, v[0:1]
	s_mov_b32 m0, s7
	s_nop 0
	global_load_lds_dwordx4 v[232:233], off
	s_mov_b32 m0, s9
	s_nop 0
	global_load_lds_dwordx4 v[234:235], off
	s_waitcnt vmcnt(8)
	s_waitcnt lgkmcnt(0)
	s_barrier
; #define PG8_STAGE(bufoff, gbase, voff) do { _Pragma("unroll") for (int _i = 0; _i < 2; ++_i) \
;         __builtin_amdgcn_global_load_lds((const unsigned*)((const char*)(gbase) + (voff)[_i]), (LAS unsigned*)(lds + (bufoff) + ldsw + _i * 8192), 16, 0, 0); } while (0)
; #define PG8_LDA(dst, b, h) do { _Pragma("unroll") for (int m = 0; m < 4; ++m) _Pragma("unroll") for (int k = 0; k < 2; ++k) dst[m][k] = *(const LAS bf16x8*)(lds + PG8_SA(b, h) + aoff + m * 2048 + k * 1024); } while (0)
; #define PG8_LDB(dst, b, h) do { _Pragma("unroll") for (int n = 0; n < 2; ++n) _Pragma("unroll") for (int k = 0; k < 2; ++k) dst[n][k] = *(const LAS bf16x8*)(lds + PG8_SB(b, h) + boff + n * 2048 + k * 1024); } while (0)
; #define PG8_MMA(ai, bj, At, Bt) do { __builtin_amdgcn_s_setprio(1); _Pragma("unroll") for (int m = 0; m < 4; ++m) _Pragma("unroll") for (int n = 0; n < 2; ++n) _Pragma("unroll") for (int k = 0; k < 2; ++k) \
;         acc[ai][bj][m][n] = __builtin_amdgcn_mfma_f32_16x16x32_bf16(Bt[n][k], At[m][k], acc[ai][bj][m][n], 0, 0, 0); __builtin_amdgcn_s_setprio(0); } while (0)
; #define PG8_WAIT_V(n) asm volatile("s_waitcnt vmcnt(" #n ")" ::: "memory")
; #define PG8_WAIT_L(n) asm volatile("s_waitcnt lgkmcnt(" #n ")" ::: "memory")
; #define PG8_BAR __builtin_amdgcn_s_barrier()
; #define PG8_SCHED __builtin_amdgcn_sched_barrier(0)
; template <class Epi>
; __device__ __forceinline__ void gemm_phase(LAS unsigned char* lds, const Gemm g, const Epi& E) {
;     ...
;             PG8_WAIT_V(8); PG8_WAIT_L(0); PG8_BAR; PG8_MMA(1, 0, At, B0); PG8_MMA(1, 1, At, B1); PG8_BAR; PG8_SCHED;
;             PG8_LDB(B0, 1, 0); PG8_LDB(B1, 1, 1); PG8_SCHED; PG8_LDA(At, 1, 0); PG8_STAGE(PG8_SA(0, 1), a2 + hstep, voffA);
;             PG8_WAIT_V(8); PG8_WAIT_L(0); PG8_BAR; PG8_MMA(0, 0, At, B0); PG8_MMA(0, 1, At, B1); PG8_BAR; PG8_SCHED;
	s_waitcnt lgkmcnt(0)
	v_mfma_f32_16x16x32_bf16 v[62:65], v[146:149], v[198:201], v[62:65]
	v_mfma_f32_16x16x32_bf16 v[54:57], v[154:157], v[198:201], v[54:57]
	v_mfma_f32_16x16x32_bf16 v[46:49], v[146:149], v[206:209], v[46:49]
	v_mfma_f32_16x16x32_bf16 v[38:41], v[154:157], v[206:209], v[38:41]
	v_mfma_f32_16x16x32_bf16 v[30:33], v[146:149], v[214:217], v[30:33]
	v_mfma_f32_16x16x32_bf16 v[22:25], v[154:157], v[214:217], v[22:25]
	v_mfma_f32_16x16x32_bf16 v[14:17], v[146:149], v[222:225], v[14:17]
	v_mfma_f32_16x16x32_bf16 v[6:9], v[154:157], v[222:225], v[6:9]
	v_mfma_f32_16x16x32_bf16 v[62:65], v[150:153], v[202:205], v[62:65]
	v_mfma_f32_16x16x32_bf16 v[54:57], v[158:161], v[202:205], v[54:57]
	v_mfma_f32_16x16x32_bf16 v[46:49], v[150:153], v[210:213], v[46:49]
	v_mfma_f32_16x16x32_bf16 v[38:41], v[158:161], v[210:213], v[38:41]
	v_mfma_f32_16x16x32_bf16 v[30:33], v[150:153], v[218:221], v[30:33]
	v_mfma_f32_16x16x32_bf16 v[22:25], v[158:161], v[218:221], v[22:25]
	v_mfma_f32_16x16x32_bf16 v[14:17], v[150:153], v[226:229], v[14:17]
	v_mfma_f32_16x16x32_bf16 v[6:9], v[158:161], v[226:229], v[6:9]
	v_mfma_f32_16x16x32_bf16 v[58:61], v[162:165], v[198:201], v[58:61]
	v_mfma_f32_16x16x32_bf16 v[50:53], v[190:193], v[198:201], v[50:53]
	v_mfma_f32_16x16x32_bf16 v[42:45], v[162:165], v[206:209], v[42:45]
	v_mfma_f32_16x16x32_bf16 v[34:37], v[190:193], v[206:209], v[34:37]
	v_mfma_f32_16x16x32_bf16 v[26:29], v[162:165], v[214:217], v[26:29]
	v_mfma_f32_16x16x32_bf16 v[18:21], v[190:193], v[214:217], v[18:21]
	v_mfma_f32_16x16x32_bf16 v[10:13], v[162:165], v[222:225], v[10:13]
	v_mfma_f32_16x16x32_bf16 v[2:5], v[190:193], v[222:225], v[2:5]
	v_mfma_f32_16x16x32_bf16 v[58:61], v[166:169], v[202:205], v[58:61]
	v_mfma_f32_16x16x32_bf16 v[50:53], v[194:197], v[202:205], v[50:53]
	v_mfma_f32_16x16x32_bf16 v[42:45], v[166:169], v[210:213], v[42:45]
	v_mfma_f32_16x16x32_bf16 v[34:37], v[194:197], v[210:213], v[34:37]
	v_mfma_f32_16x16x32_bf16 v[26:29], v[166:169], v[218:221], v[26:29]
	v_mfma_f32_16x16x32_bf16 v[18:21], v[194:197], v[218:221], v[18:21]
	v_mfma_f32_16x16x32_bf16 v[10:13], v[166:169], v[226:229], v[10:13]
	v_mfma_f32_16x16x32_bf16 v[2:5], v[194:197], v[226:229], v[2:5]
	s_barrier
	s_add_i32 s25, 0, 0x18000
	s_add_i32 s72, 0, 0x1c000
	v_add_u32_e32 v158, s25, v144
	v_add_u32_e32 v189, s72, v144
	ds_read_b128 v[146:149], v158
	ds_read_b128 v[150:153], v158 offset:1024
	ds_read_b128 v[154:157], v158 offset:2048
	ds_read_b128 v[158:161], v158 offset:3072
	ds_read_b128 v[162:165], v189
	ds_read_b128 v[166:169], v189 offset:1024
	ds_read_b128 v[190:193], v189 offset:2048
	ds_read_b128 v[194:197], v189 offset:3072
	s_add_u32 s70, s70, 0x40000
	s_addc_u32 s71, s71, 0
	s_mov_b32 m0, s45
	v_lshl_add_u64 v[236:237], s[70:71], 0, v[0:1]
	ds_read_b128 v[198:201], v145 offset:32768
	ds_read_b128 v[202:205], v145 offset:33792
	ds_read_b128 v[206:209], v145 offset:34816
	ds_read_b128 v[210:213], v145 offset:35840
	ds_read_b128 v[214:217], v145 offset:36864
	ds_read_b128 v[218:221], v145 offset:37888
	ds_read_b128 v[222:225], v145 offset:38912
	ds_read_b128 v[226:229], v145 offset:39936
	global_load_lds_dwordx4 v[236:237], off
	v_lshl_add_u64 v[236:237], s[70:71], 0, v[130:131]
	s_mov_b32 m0, s52
	s_nop 0
	global_load_lds_dwordx4 v[236:237], off
	s_waitcnt vmcnt(8)
	s_waitcnt lgkmcnt(0)
	s_barrier
	s_waitcnt lgkmcnt(0)
	v_mfma_f32_16x16x32_bf16 v[126:129], v[146:149], v[198:201], v[126:129]
	v_mfma_f32_16x16x32_bf16 v[118:121], v[154:157], v[198:201], v[118:121]
	v_mfma_f32_16x16x32_bf16 v[110:113], v[146:149], v[206:209], v[110:113]
	v_mfma_f32_16x16x32_bf16 v[102:105], v[154:157], v[206:209], v[102:105]
	v_mfma_f32_16x16x32_bf16 v[94:97], v[146:149], v[214:217], v[94:97]
	v_mfma_f32_16x16x32_bf16 v[86:89], v[154:157], v[214:217], v[86:89]
	v_mfma_f32_16x16x32_bf16 v[78:81], v[146:149], v[222:225], v[78:81]
	v_mfma_f32_16x16x32_bf16 v[70:73], v[154:157], v[222:225], v[70:73]
	v_mfma_f32_16x16x32_bf16 v[126:129], v[150:153], v[202:205], v[126:129]
	v_mfma_f32_16x16x32_bf16 v[118:121], v[158:161], v[202:205], v[118:121]
	v_mfma_f32_16x16x32_bf16 v[110:113], v[150:153], v[210:213], v[110:113]
	v_mfma_f32_16x16x32_bf16 v[102:105], v[158:161], v[210:213], v[102:105]
	v_mfma_f32_16x16x32_bf16 v[94:97], v[150:153], v[218:221], v[94:97]
	v_mfma_f32_16x16x32_bf16 v[86:89], v[158:161], v[218:221], v[86:89]
	v_mfma_f32_16x16x32_bf16 v[78:81], v[150:153], v[226:229], v[78:81]
	v_mfma_f32_16x16x32_bf16 v[70:73], v[158:161], v[226:229], v[70:73]
	v_mfma_f32_16x16x32_bf16 v[122:125], v[162:165], v[198:201], v[122:125]
	v_mfma_f32_16x16x32_bf16 v[114:117], v[190:193], v[198:201], v[114:117]
	v_mfma_f32_16x16x32_bf16 v[106:109], v[162:165], v[206:209], v[106:109]
	v_mfma_f32_16x16x32_bf16 v[98:101], v[190:193], v[206:209], v[98:101]
	v_mfma_f32_16x16x32_bf16 v[90:93], v[162:165], v[214:217], v[90:93]
	v_mfma_f32_16x16x32_bf16 v[82:85], v[190:193], v[214:217], v[82:85]
	v_mfma_f32_16x16x32_bf16 v[74:77], v[162:165], v[222:225], v[74:77]
	v_mfma_f32_16x16x32_bf16 v[66:69], v[190:193], v[222:225], v[66:69]
	v_mfma_f32_16x16x32_bf16 v[122:125], v[166:169], v[202:205], v[122:125]
	v_mfma_f32_16x16x32_bf16 v[114:117], v[194:197], v[202:205], v[114:117]
	v_mfma_f32_16x16x32_bf16 v[106:109], v[166:169], v[210:213], v[106:109]
	v_mfma_f32_16x16x32_bf16 v[98:101], v[194:197], v[210:213], v[98:101]
	v_mfma_f32_16x16x32_bf16 v[90:93], v[166:169], v[218:221], v[90:93]
	v_mfma_f32_16x16x32_bf16 v[82:85], v[194:197], v[218:221], v[82:85]
	v_mfma_f32_16x16x32_bf16 v[74:77], v[166:169], v[226:229], v[74:77]
	v_mfma_f32_16x16x32_bf16 v[66:69], v[194:197], v[226:229], v[66:69]
	s_barrier
; #define PG8_STAGE(bufoff, gbase, voff) do { _Pragma("unroll") for (int _i = 0; _i < 2; ++_i) \
;         __builtin_amdgcn_global_load_lds((const unsigned*)((const char*)(gbase) + (voff)[_i]), (LAS unsigned*)(lds + (bufoff) + ldsw + _i * 8192), 16, 0, 0); } while (0)
; #define PG8_LDA(dst, b, h) do { _Pragma("unroll") for (int m = 0; m < 4; ++m) _Pragma("unroll") for (int k = 0; k < 2; ++k) dst[m][k] = *(const LAS bf16x8*)(lds + PG8_SA(b, h) + aoff + m * 2048 + k * 1024); } while (0)
; #define PG8_MMA(ai, bj, At, Bt) do { __builtin_amdgcn_s_setprio(1); _Pragma("unroll") for (int m = 0; m < 4; ++m) _Pragma("unroll") for (int n = 0; n < 2; ++n) _Pragma("unroll") for (int k = 0; k < 2; ++k) \
;         acc[ai][bj][m][n] = __builtin_amdgcn_mfma_f32_16x16x32_bf16(Bt[n][k], At[m][k], acc[ai][bj][m][n], 0, 0, 0); __builtin_amdgcn_s_setprio(0); } while (0)
; #define PG8_WAIT_V(n) asm volatile("s_waitcnt vmcnt(" #n ")" ::: "memory")
; #define PG8_WAIT_L(n) asm volatile("s_waitcnt lgkmcnt(" #n ")" ::: "memory")
; #define PG8_BAR __builtin_amdgcn_s_barrier()
; #define PG8_SCHED __builtin_amdgcn_sched_barrier(0)
; template <class Epi>
; __device__ __forceinline__ void gemm_phase(LAS unsigned char* lds, const Gemm g, const Epi& E) {
;     ...
;             PG8_LDA(At, 1, 1); PG8_STAGE(PG8_SB(1, 0), b3, voffA); PG8_STAGE(PG8_SB(1, 1), b3 + hstep, voffA); PG8_STAGE(PG8_SA(1, 0), a3, voffA);
;             PG8_WAIT_V(8); PG8_WAIT_L(0); PG8_BAR; PG8_MMA(1, 0, At, B0); PG8_MMA(1, 1, At, B1); PG8_BAR; PG8_SCHED;
;         }
	s_add_i32 s25, s25, s2
	v_lshl_add_u64 v[136:137], v[136:137], 0, s[80:81]
	s_mov_b32 m0, s25
	ds_read_b128 v[198:201], v145 offset:49152
	ds_read_b128 v[202:205], v145 offset:50176
	ds_read_b128 v[206:209], v145 offset:51200
	ds_read_b128 v[210:213], v145 offset:52224
	ds_read_b128 v[214:217], v145 offset:53248
	ds_read_b128 v[218:221], v145 offset:54272
	ds_read_b128 v[222:225], v145 offset:55296
	ds_read_b128 v[226:229], v145 offset:56320
	global_load_lds_dwordx4 v[136:137], off
	s_add_i32 m0, s25, 0x2000
	s_add_u32 s4, s4, 0x40080
	v_lshl_add_u64 v[136:137], v[230:231], 0, s[80:81]
	s_addc_u32 s5, s5, 0
	s_add_i32 s25, s72, s2
	global_load_lds_dwordx4 v[136:137], off
	v_lshl_add_u64 v[136:137], s[4:5], 0, v[0:1]
	s_mov_b32 m0, s25
	s_nop 0
	global_load_lds_dwordx4 v[136:137], off
	v_lshl_add_u64 v[136:137], s[4:5], 0, v[130:131]
	s_add_i32 m0, s25, 0x2000
	s_nop 0
	global_load_lds_dwordx4 v[136:137], off
	v_lshl_add_u64 v[136:137], v[232:233], 0, s[80:81]
	s_mov_b32 m0, s75
	s_nop 0
	global_load_lds_dwordx4 v[136:137], off
	v_lshl_add_u64 v[136:137], v[234:235], 0, s[80:81]
	s_mov_b32 m0, s76
	s_nop 0
	global_load_lds_dwordx4 v[136:137], off
	s_waitcnt vmcnt(8)
	s_waitcnt lgkmcnt(0)
	s_barrier
	s_waitcnt lgkmcnt(0)
	v_mfma_f32_16x16x32_bf16 v[62:65], v[146:149], v[198:201], v[62:65]
	v_mfma_f32_16x16x32_bf16 v[54:57], v[154:157], v[198:201], v[54:57]
	v_mfma_f32_16x16x32_bf16 v[46:49], v[146:149], v[206:209], v[46:49]
	v_mfma_f32_16x16x32_bf16 v[38:41], v[154:157], v[206:209], v[38:41]
	v_mfma_f32_16x16x32_bf16 v[30:33], v[146:149], v[214:217], v[30:33]
	v_mfma_f32_16x16x32_bf16 v[22:25], v[154:157], v[214:217], v[22:25]
	v_mfma_f32_16x16x32_bf16 v[14:17], v[146:149], v[222:225], v[14:17]
	v_mfma_f32_16x16x32_bf16 v[6:9], v[154:157], v[222:225], v[6:9]
	v_mfma_f32_16x16x32_bf16 v[62:65], v[150:153], v[202:205], v[62:65]
	v_mfma_f32_16x16x32_bf16 v[54:57], v[158:161], v[202:205], v[54:57]
	v_mfma_f32_16x16x32_bf16 v[46:49], v[150:153], v[210:213], v[46:49]
	v_mfma_f32_16x16x32_bf16 v[38:41], v[158:161], v[210:213], v[38:41]
	v_mfma_f32_16x16x32_bf16 v[30:33], v[150:153], v[218:221], v[30:33]
	v_mfma_f32_16x16x32_bf16 v[22:25], v[158:161], v[218:221], v[22:25]
	v_mfma_f32_16x16x32_bf16 v[14:17], v[150:153], v[226:229], v[14:17]
	v_mfma_f32_16x16x32_bf16 v[6:9], v[158:161], v[226:229], v[6:9]
	v_mfma_f32_16x16x32_bf16 v[58:61], v[162:165], v[198:201], v[58:61]
	v_mfma_f32_16x16x32_bf16 v[50:53], v[190:193], v[198:201], v[50:53]
	v_mfma_f32_16x16x32_bf16 v[42:45], v[162:165], v[206:209], v[42:45]
	v_mfma_f32_16x16x32_bf16 v[34:37], v[190:193], v[206:209], v[34:37]
	v_mfma_f32_16x16x32_bf16 v[26:29], v[162:165], v[214:217], v[26:29]
	v_mfma_f32_16x16x32_bf16 v[18:21], v[190:193], v[214:217], v[18:21]
	v_mfma_f32_16x16x32_bf16 v[10:13], v[162:165], v[222:225], v[10:13]
	v_mfma_f32_16x16x32_bf16 v[2:5], v[190:193], v[222:225], v[2:5]
	v_mfma_f32_16x16x32_bf16 v[58:61], v[166:169], v[202:205], v[58:61]
	v_mfma_f32_16x16x32_bf16 v[50:53], v[194:197], v[202:205], v[50:53]
	v_mfma_f32_16x16x32_bf16 v[42:45], v[166:169], v[210:213], v[42:45]
	v_mfma_f32_16x16x32_bf16 v[34:37], v[194:197], v[210:213], v[34:37]
	v_mfma_f32_16x16x32_bf16 v[26:29], v[166:169], v[218:221], v[26:29]
	v_mfma_f32_16x16x32_bf16 v[18:21], v[194:197], v[218:221], v[18:21]
	v_mfma_f32_16x16x32_bf16 v[10:13], v[166:169], v[226:229], v[10:13]
	v_mfma_f32_16x16x32_bf16 v[2:5], v[194:197], v[226:229], v[2:5]
	s_barrier
	s_add_u32 s68, s68, 0x100
	s_addc_u32 s69, s69, 0
	s_add_u32 s93, s93, 0x100
	s_addc_u32 vcc_lo, vcc_lo, 0
	s_cmp_ge_i32 vcc_hi, s37
	s_mov_b32 s4, vcc_hi
	s_cbranch_scc0 .LBB0_441

; #define PG8_STAGE(bufoff, gbase, voff) do { _Pragma("unroll") for (int _i = 0; _i < 2; ++_i) \
;         __builtin_amdgcn_global_load_lds((const unsigned*)((const char*)(gbase) + (voff)[_i]), (LAS unsigned*)(lds + (bufoff) + ldsw + _i * 8192), 16, 0, 0); } while (0)
; #define PG8_LDA(dst, b, h) do { _Pragma("unroll") for (int m = 0; m < 4; ++m) _Pragma("unroll") for (int k = 0; k < 2; ++k) dst[m][k] = *(const LAS bf16x8*)(lds + PG8_SA(b, h) + aoff + m * 2048 + k * 1024); } while (0)
; #define PG8_LDB(dst, b, h) do { _Pragma("unroll") for (int n = 0; n < 2; ++n) _Pragma("unroll") for (int k = 0; k < 2; ++k) dst[n][k] = *(const LAS bf16x8*)(lds + PG8_SB(b, h) + boff + n * 2048 + k * 1024); } while (0)
; #define PG8_MMA(ai, bj, At, Bt) do { __builtin_amdgcn_s_setprio(1); _Pragma("unroll") for (int m = 0; m < 4; ++m) _Pragma("unroll") for (int n = 0; n < 2; ++n) _Pragma("unroll") for (int k = 0; k < 2; ++k) \
;         acc[ai][bj][m][n] = __builtin_amdgcn_mfma_f32_16x16x32_bf16(Bt[n][k], At[m][k], acc[ai][bj][m][n], 0, 0, 0); __builtin_amdgcn_s_setprio(0); } while (0)
; #define PG8_WAIT_V(n) asm volatile("s_waitcnt vmcnt(" #n ")" ::: "memory")
; #define PG8_WAIT_L(n) asm volatile("s_waitcnt lgkmcnt(" #n ")" ::: "memory")
; #define PG8_BAR __builtin_amdgcn_s_barrier()
; #define PG8_SCHED __builtin_amdgcn_sched_barrier(0)
; template <class Epi>
; __device__ __forceinline__ void gemm_phase(LAS unsigned char* lds, const Gemm g, const Epi& E) {
;     ...
;         for (int t = 0; t < nt; t += 2) {
;             const bool last = (t == nt - 2);
;             const char* a1 = cA + (size_t)(t + 1) * kstep;
;             const char* a2 = last ? nA : cA + (size_t)(t + 2) * kstep; const char* b2 = last ? nB : cB + (size_t)(t + 2) * kstep;
;             const char* a3 = a2 + kstep; const char* b3 = b2 + kstep;
;             PG8_LDB(B0, 0, 0); PG8_LDB(B1, 0, 1); PG8_SCHED; PG8_LDA(At, 0, 0); PG8_STAGE(PG8_SA(1, 1), a1 + hstep, voffA);
;             PG8_WAIT_V(8); PG8_WAIT_L(0); PG8_BAR; PG8_MMA(0, 0, At, B0); PG8_MMA(0, 1, At, B1); PG8_BAR; PG8_SCHED;
;             PG8_LDA(At, 0, 1); PG8_STAGE(PG8_SB(0, 0), b2, voffA); PG8_STAGE(PG8_SB(0, 1), b2 + hstep, voffA); PG8_STAGE(PG8_SA(0, 0), a2, voffA);
;             PG8_WAIT_V(8); PG8_WAIT_L(0); PG8_BAR; PG8_MMA(1, 0, At, B0); PG8_MMA(1, 1, At, B1); PG8_BAR; PG8_SCHED;
.LBB0_473:
	s_add_i32 s61, s4, 2
	s_add_u32 s5, s10, 0xfffc0080
	s_addc_u32 s25, s11, -1
	s_cmp_eq_u32 s2, s4
	s_cselect_b32 s73, s67, s25
	s_cselect_b32 s72, s66, s5
	v_add_u32_e32 v0, s21, v160
	s_cselect_b32 s5, s69, s45
	s_cselect_b32 s4, s68, s15
	s_add_i32 s25, 0, 0x14000
	ds_read_b128 v[146:149], v0
	ds_read_b128 v[150:153], v0 offset:1024
	ds_read_b128 v[154:157], v0 offset:2048
	ds_read_b128 v[162:165], v0 offset:3072
	v_add_u32_e32 v0, s25, v160
	ds_read_b128 v[166:169], v0
	ds_read_b128 v[190:193], v0 offset:1024
	ds_read_b128 v[194:197], v0 offset:2048
	ds_read_b128 v[198:201], v0 offset:3072
	v_lshl_add_u64 v[2:3], s[10:11], 0, v[136:137]
	s_add_i32 m0, s7, 0xc000
	ds_read_b128 v[202:205], v161
	ds_read_b128 v[206:209], v161 offset:1024
	ds_read_b128 v[210:213], v161 offset:2048
	ds_read_b128 v[214:217], v161 offset:3072
	ds_read_b128 v[218:221], v161 offset:4096
	ds_read_b128 v[222:225], v161 offset:5120
	ds_read_b128 v[226:229], v161 offset:6144
	ds_read_b128 v[230:233], v161 offset:7168
	global_load_lds_dwordx4 v[2:3], off
	v_lshl_add_u64 v[2:3], s[10:11], 0, v[144:145]
	s_add_i32 m0, s7, 0xe000
	s_nop 0
	global_load_lds_dwordx4 v[2:3], off
	s_waitcnt vmcnt(8)
	s_waitcnt lgkmcnt(0)
	s_barrier
	s_waitcnt lgkmcnt(0)
	v_mfma_f32_16x16x32_bf16 v[128:131], v[146:149], v[202:205], v[128:131]
	v_mfma_f32_16x16x32_bf16 v[124:127], v[154:157], v[202:205], v[124:127]
	v_mfma_f32_16x16x32_bf16 v[120:123], v[146:149], v[210:213], v[120:123]
	v_mfma_f32_16x16x32_bf16 v[116:119], v[154:157], v[210:213], v[116:119]
	v_mfma_f32_16x16x32_bf16 v[112:115], v[146:149], v[218:221], v[112:115]
	v_mfma_f32_16x16x32_bf16 v[108:111], v[154:157], v[218:221], v[108:111]
	v_mfma_f32_16x16x32_bf16 v[104:107], v[146:149], v[226:229], v[104:107]
	v_mfma_f32_16x16x32_bf16 v[100:103], v[154:157], v[226:229], v[100:103]
	v_mfma_f32_16x16x32_bf16 v[128:131], v[150:153], v[206:209], v[128:131]
	v_mfma_f32_16x16x32_bf16 v[124:127], v[162:165], v[206:209], v[124:127]
	v_mfma_f32_16x16x32_bf16 v[120:123], v[150:153], v[214:217], v[120:123]
	v_mfma_f32_16x16x32_bf16 v[116:119], v[162:165], v[214:217], v[116:119]
	v_mfma_f32_16x16x32_bf16 v[112:115], v[150:153], v[222:225], v[112:115]
	v_mfma_f32_16x16x32_bf16 v[108:111], v[162:165], v[222:225], v[108:111]
	v_mfma_f32_16x16x32_bf16 v[104:107], v[150:153], v[230:233], v[104:107]
	v_mfma_f32_16x16x32_bf16 v[100:103], v[162:165], v[230:233], v[100:103]
	v_mfma_f32_16x16x32_bf16 v[96:99], v[166:169], v[202:205], v[96:99]
	v_mfma_f32_16x16x32_bf16 v[92:95], v[194:197], v[202:205], v[92:95]
	v_mfma_f32_16x16x32_bf16 v[88:91], v[166:169], v[210:213], v[88:91]
	v_mfma_f32_16x16x32_bf16 v[84:87], v[194:197], v[210:213], v[84:87]
	v_mfma_f32_16x16x32_bf16 v[80:83], v[166:169], v[218:221], v[80:83]
	v_mfma_f32_16x16x32_bf16 v[76:79], v[194:197], v[218:221], v[76:79]
	v_mfma_f32_16x16x32_bf16 v[72:75], v[166:169], v[226:229], v[72:75]
	v_mfma_f32_16x16x32_bf16 v[68:71], v[194:197], v[226:229], v[68:71]
	v_mfma_f32_16x16x32_bf16 v[96:99], v[190:193], v[206:209], v[96:99]
	v_mfma_f32_16x16x32_bf16 v[92:95], v[198:201], v[206:209], v[92:95]
	v_mfma_f32_16x16x32_bf16 v[88:91], v[190:193], v[214:217], v[88:91]
	v_mfma_f32_16x16x32_bf16 v[84:87], v[198:201], v[214:217], v[84:87]
	v_mfma_f32_16x16x32_bf16 v[80:83], v[190:193], v[222:225], v[80:83]
	v_mfma_f32_16x16x32_bf16 v[76:79], v[198:201], v[222:225], v[76:79]
	v_mfma_f32_16x16x32_bf16 v[72:75], v[190:193], v[230:233], v[72:75]
	v_mfma_f32_16x16x32_bf16 v[68:71], v[198:201], v[230:233], v[68:71]
	s_barrier
	s_add_i32 s63, s21, s20
	v_lshl_add_u64 v[158:159], s[4:5], 0, v[134:135]
	s_mov_b32 m0, s63
	ds_read_b128 v[202:205], v161 offset:16384
	ds_read_b128 v[206:209], v161 offset:17408
	ds_read_b128 v[210:213], v161 offset:18432
	ds_read_b128 v[214:217], v161 offset:19456
	ds_read_b128 v[218:221], v161 offset:20480
	ds_read_b128 v[222:225], v161 offset:21504
	ds_read_b128 v[226:229], v161 offset:22528
	ds_read_b128 v[230:233], v161 offset:23552
	global_load_lds_dwordx4 v[158:159], off
	s_add_i32 m0, s63, 0x2000
	s_add_u32 vcc_lo, s4, 0x40000
	v_lshl_add_u64 v[234:235], s[4:5], 0, v[132:133]
	s_addc_u32 vcc_hi, s5, 0
	s_add_i32 s25, s25, s20
	global_load_lds_dwordx4 v[234:235], off
	v_lshl_add_u64 v[2:3], vcc, 0, v[134:135]
	s_mov_b32 m0, s25
	v_lshl_add_u64 v[236:237], s[72:73], 0, v[134:135]
	global_load_lds_dwordx4 v[2:3], off
	v_lshl_add_u64 v[2:3], vcc, 0, v[132:133]
	s_add_i32 m0, s25, 0x2000
	v_lshl_add_u64 v[238:239], s[72:73], 0, v[132:133]
	global_load_lds_dwordx4 v[2:3], off
	s_mov_b32 m0, s7
	s_nop 0
	global_load_lds_dwordx4 v[236:237], off
	s_mov_b32 m0, s13
	s_nop 0
	global_load_lds_dwordx4 v[238:239], off
	s_waitcnt vmcnt(8)
	s_waitcnt lgkmcnt(0)
	s_barrier
; #define PG8_STAGE(bufoff, gbase, voff) do { _Pragma("unroll") for (int _i = 0; _i < 2; ++_i) \
;         __builtin_amdgcn_global_load_lds((const unsigned*)((const char*)(gbase) + (voff)[_i]), (LAS unsigned*)(lds + (bufoff) + ldsw + _i * 8192), 16, 0, 0); } while (0)
; #define PG8_LDA(dst, b, h) do { _Pragma("unroll") for (int m = 0; m < 4; ++m) _Pragma("unroll") for (int k = 0; k < 2; ++k) dst[m][k] = *(const LAS bf16x8*)(lds + PG8_SA(b, h) + aoff + m * 2048 + k * 1024); } while (0)
; #define PG8_LDB(dst, b, h) do { _Pragma("unroll") for (int n = 0; n < 2; ++n) _Pragma("unroll") for (int k = 0; k < 2; ++k) dst[n][k] = *(const LAS bf16x8*)(lds + PG8_SB(b, h) + boff + n * 2048 + k * 1024); } while (0)
; #define PG8_MMA(ai, bj, At, Bt) do { __builtin_amdgcn_s_setprio(1); _Pragma("unroll") for (int m = 0; m < 4; ++m) _Pragma("unroll") for (int n = 0; n < 2; ++n) _Pragma("unroll") for (int k = 0; k < 2; ++k) \
;         acc[ai][bj][m][n] = __builtin_amdgcn_mfma_f32_16x16x32_bf16(Bt[n][k], At[m][k], acc[ai][bj][m][n], 0, 0, 0); __builtin_amdgcn_s_setprio(0); } while (0)
; #define PG8_WAIT_V(n) asm volatile("s_waitcnt vmcnt(" #n ")" ::: "memory")
; #define PG8_WAIT_L(n) asm volatile("s_waitcnt lgkmcnt(" #n ")" ::: "memory")
; #define PG8_BAR __builtin_amdgcn_s_barrier()
; #define PG8_SCHED __builtin_amdgcn_sched_barrier(0)
; template <class Epi>
; __device__ __forceinline__ void gemm_phase(LAS unsigned char* lds, const Gemm g, const Epi& E) {
;     ...
;             PG8_WAIT_V(8); PG8_WAIT_L(0); PG8_BAR; PG8_MMA(1, 0, At, B0); PG8_MMA(1, 1, At, B1); PG8_BAR; PG8_SCHED;
;             PG8_LDB(B0, 1, 0); PG8_LDB(B1, 1, 1); PG8_SCHED; PG8_LDA(At, 1, 0); PG8_STAGE(PG8_SA(0, 1), a2 + hstep, voffA);
;             PG8_WAIT_V(8); PG8_WAIT_L(0); PG8_BAR; PG8_MMA(0, 0, At, B0); PG8_MMA(0, 1, At, B1); PG8_BAR; PG8_SCHED;
	s_waitcnt lgkmcnt(0)
	v_mfma_f32_16x16x32_bf16 v[64:67], v[146:149], v[202:205], v[64:67]
	v_mfma_f32_16x16x32_bf16 v[60:63], v[154:157], v[202:205], v[60:63]
	v_mfma_f32_16x16x32_bf16 v[56:59], v[146:149], v[210:213], v[56:59]
	v_mfma_f32_16x16x32_bf16 v[52:55], v[154:157], v[210:213], v[52:55]
	v_mfma_f32_16x16x32_bf16 v[48:51], v[146:149], v[218:221], v[48:51]
	v_mfma_f32_16x16x32_bf16 v[44:47], v[154:157], v[218:221], v[44:47]
	v_mfma_f32_16x16x32_bf16 v[40:43], v[146:149], v[226:229], v[40:43]
	v_mfma_f32_16x16x32_bf16 v[36:39], v[154:157], v[226:229], v[36:39]
	v_mfma_f32_16x16x32_bf16 v[64:67], v[150:153], v[206:209], v[64:67]
	v_mfma_f32_16x16x32_bf16 v[60:63], v[162:165], v[206:209], v[60:63]
	v_mfma_f32_16x16x32_bf16 v[56:59], v[150:153], v[214:217], v[56:59]
	v_mfma_f32_16x16x32_bf16 v[52:55], v[162:165], v[214:217], v[52:55]
	v_mfma_f32_16x16x32_bf16 v[48:51], v[150:153], v[222:225], v[48:51]
	v_mfma_f32_16x16x32_bf16 v[44:47], v[162:165], v[222:225], v[44:47]
	v_mfma_f32_16x16x32_bf16 v[40:43], v[150:153], v[230:233], v[40:43]
	v_mfma_f32_16x16x32_bf16 v[36:39], v[162:165], v[230:233], v[36:39]
	v_mfma_f32_16x16x32_bf16 v[32:35], v[166:169], v[202:205], v[32:35]
	v_mfma_f32_16x16x32_bf16 v[28:31], v[194:197], v[202:205], v[28:31]
	v_mfma_f32_16x16x32_bf16 v[24:27], v[166:169], v[210:213], v[24:27]
	v_mfma_f32_16x16x32_bf16 v[20:23], v[194:197], v[210:213], v[20:23]
	v_mfma_f32_16x16x32_bf16 v[16:19], v[166:169], v[218:221], v[16:19]
	v_mfma_f32_16x16x32_bf16 v[12:15], v[194:197], v[218:221], v[12:15]
	v_mfma_f32_16x16x32_bf16 v[8:11], v[166:169], v[226:229], v[8:11]
	v_mfma_f32_16x16x32_bf16 v[2:5], v[194:197], v[226:229], v[4:7]
	v_mfma_f32_16x16x32_bf16 v[32:35], v[190:193], v[206:209], v[32:35]
	v_mfma_f32_16x16x32_bf16 v[28:31], v[198:201], v[206:209], v[28:31]
	v_mfma_f32_16x16x32_bf16 v[24:27], v[190:193], v[214:217], v[24:27]
	v_mfma_f32_16x16x32_bf16 v[20:23], v[198:201], v[214:217], v[20:23]
	v_mfma_f32_16x16x32_bf16 v[16:19], v[190:193], v[222:225], v[16:19]
	v_mfma_f32_16x16x32_bf16 v[12:15], v[198:201], v[222:225], v[12:15]
	v_mfma_f32_16x16x32_bf16 v[8:11], v[190:193], v[230:233], v[8:11]
	v_mfma_f32_16x16x32_bf16 v[2:5], v[198:201], v[230:233], v[2:5]
	s_barrier
	s_add_i32 s25, 0, 0x18000
	v_add_u32_e32 v0, s25, v160
	s_add_i32 s63, 0, 0x1c000
	ds_read_b128 v[146:149], v0
	ds_read_b128 v[150:153], v0 offset:1024
	ds_read_b128 v[154:157], v0 offset:2048
	ds_read_b128 v[162:165], v0 offset:3072
	v_add_u32_e32 v0, s63, v160
	ds_read_b128 v[166:169], v0
	ds_read_b128 v[190:193], v0 offset:1024
	ds_read_b128 v[194:197], v0 offset:2048
	ds_read_b128 v[198:201], v0 offset:3072
	s_add_u32 s72, s72, 0x40000
	s_addc_u32 s73, s73, 0
	s_mov_b32 m0, s75
	v_lshl_add_u64 v[6:7], s[72:73], 0, v[134:135]
	ds_read_b128 v[202:205], v161 offset:32768
	ds_read_b128 v[206:209], v161 offset:33792
	ds_read_b128 v[210:213], v161 offset:34816
	ds_read_b128 v[214:217], v161 offset:35840
	ds_read_b128 v[218:221], v161 offset:36864
	ds_read_b128 v[222:225], v161 offset:37888
	ds_read_b128 v[226:229], v161 offset:38912
	ds_read_b128 v[230:233], v161 offset:39936
	global_load_lds_dwordx4 v[6:7], off
	v_lshl_add_u64 v[6:7], s[72:73], 0, v[132:133]
	s_mov_b32 m0, s76
	s_nop 0
	global_load_lds_dwordx4 v[6:7], off
	s_waitcnt vmcnt(8)
	s_waitcnt lgkmcnt(0)
	s_barrier
	s_waitcnt lgkmcnt(0)
	v_mfma_f32_16x16x32_bf16 v[128:131], v[146:149], v[202:205], v[128:131]
	v_mfma_f32_16x16x32_bf16 v[124:127], v[154:157], v[202:205], v[124:127]
	v_mfma_f32_16x16x32_bf16 v[120:123], v[146:149], v[210:213], v[120:123]
	v_mfma_f32_16x16x32_bf16 v[116:119], v[154:157], v[210:213], v[116:119]
	v_mfma_f32_16x16x32_bf16 v[112:115], v[146:149], v[218:221], v[112:115]
	v_mfma_f32_16x16x32_bf16 v[108:111], v[154:157], v[218:221], v[108:111]
	v_mfma_f32_16x16x32_bf16 v[104:107], v[146:149], v[226:229], v[104:107]
	v_mfma_f32_16x16x32_bf16 v[100:103], v[154:157], v[226:229], v[100:103]
	v_mfma_f32_16x16x32_bf16 v[128:131], v[150:153], v[206:209], v[128:131]
	v_mfma_f32_16x16x32_bf16 v[124:127], v[162:165], v[206:209], v[124:127]
	v_mfma_f32_16x16x32_bf16 v[120:123], v[150:153], v[214:217], v[120:123]
	v_mfma_f32_16x16x32_bf16 v[116:119], v[162:165], v[214:217], v[116:119]
	v_mfma_f32_16x16x32_bf16 v[112:115], v[150:153], v[222:225], v[112:115]
	v_mfma_f32_16x16x32_bf16 v[108:111], v[162:165], v[222:225], v[108:111]
	v_mfma_f32_16x16x32_bf16 v[104:107], v[150:153], v[230:233], v[104:107]
	v_mfma_f32_16x16x32_bf16 v[100:103], v[162:165], v[230:233], v[100:103]
	v_mfma_f32_16x16x32_bf16 v[96:99], v[166:169], v[202:205], v[96:99]
	v_mfma_f32_16x16x32_bf16 v[92:95], v[194:197], v[202:205], v[92:95]
	v_mfma_f32_16x16x32_bf16 v[88:91], v[166:169], v[210:213], v[88:91]
	v_mfma_f32_16x16x32_bf16 v[84:87], v[194:197], v[210:213], v[84:87]
	v_mfma_f32_16x16x32_bf16 v[80:83], v[166:169], v[218:221], v[80:83]
	v_mfma_f32_16x16x32_bf16 v[76:79], v[194:197], v[218:221], v[76:79]
	v_mfma_f32_16x16x32_bf16 v[72:75], v[166:169], v[226:229], v[72:75]
	v_mfma_f32_16x16x32_bf16 v[68:71], v[194:197], v[226:229], v[68:71]
	v_mfma_f32_16x16x32_bf16 v[96:99], v[190:193], v[206:209], v[96:99]
	v_mfma_f32_16x16x32_bf16 v[92:95], v[198:201], v[206:209], v[92:95]
	v_mfma_f32_16x16x32_bf16 v[88:91], v[190:193], v[214:217], v[88:91]
	v_mfma_f32_16x16x32_bf16 v[84:87], v[198:201], v[214:217], v[84:87]
	v_mfma_f32_16x16x32_bf16 v[80:83], v[190:193], v[222:225], v[80:83]
	v_mfma_f32_16x16x32_bf16 v[76:79], v[198:201], v[222:225], v[76:79]
	v_mfma_f32_16x16x32_bf16 v[72:75], v[190:193], v[230:233], v[72:75]
	v_mfma_f32_16x16x32_bf16 v[68:71], v[198:201], v[230:233], v[68:71]
	s_barrier
; #define PG8_STAGE(bufoff, gbase, voff) do { _Pragma("unroll") for (int _i = 0; _i < 2; ++_i) \
;         __builtin_amdgcn_global_load_lds((const unsigned*)((const char*)(gbase) + (voff)[_i]), (LAS unsigned*)(lds + (bufoff) + ldsw + _i * 8192), 16, 0, 0); } while (0)
; #define PG8_LDA(dst, b, h) do { _Pragma("unroll") for (int m = 0; m < 4; ++m) _Pragma("unroll") for (int k = 0; k < 2; ++k) dst[m][k] = *(const LAS bf16x8*)(lds + PG8_SA(b, h) + aoff + m * 2048 + k * 1024); } while (0)
; #define PG8_MMA(ai, bj, At, Bt) do { __builtin_amdgcn_s_setprio(1); _Pragma("unroll") for (int m = 0; m < 4; ++m) _Pragma("unroll") for (int n = 0; n < 2; ++n) _Pragma("unroll") for (int k = 0; k < 2; ++k) \
;         acc[ai][bj][m][n] = __builtin_amdgcn_mfma_f32_16x16x32_bf16(Bt[n][k], At[m][k], acc[ai][bj][m][n], 0, 0, 0); __builtin_amdgcn_s_setprio(0); } while (0)
; #define PG8_WAIT_V(n) asm volatile("s_waitcnt vmcnt(" #n ")" ::: "memory")
; #define PG8_WAIT_L(n) asm volatile("s_waitcnt lgkmcnt(" #n ")" ::: "memory")
; #define PG8_BAR __builtin_amdgcn_s_barrier()
; #define PG8_SCHED __builtin_amdgcn_sched_barrier(0)
; template <class Epi>
; __device__ __forceinline__ void gemm_phase(LAS unsigned char* lds, const Gemm g, const Epi& E) {
;     ...
;             PG8_LDA(At, 1, 1); PG8_STAGE(PG8_SB(1, 0), b3, voffA); PG8_STAGE(PG8_SB(1, 1), b3 + hstep, voffA); PG8_STAGE(PG8_SA(1, 0), a3, voffA);
;             PG8_WAIT_V(8); PG8_WAIT_L(0); PG8_BAR; PG8_MMA(1, 0, At, B0); PG8_MMA(1, 1, At, B1); PG8_BAR; PG8_SCHED;
;         }
	s_add_i32 s25, s25, s20
	v_lshl_add_u64 v[6:7], v[158:159], 0, s[80:81]
	s_mov_b32 m0, s25
	ds_read_b128 v[202:205], v161 offset:49152
	ds_read_b128 v[206:209], v161 offset:50176
	ds_read_b128 v[210:213], v161 offset:51200
	ds_read_b128 v[214:217], v161 offset:52224
	ds_read_b128 v[218:221], v161 offset:53248
	ds_read_b128 v[222:225], v161 offset:54272
	ds_read_b128 v[226:229], v161 offset:55296
	ds_read_b128 v[230:233], v161 offset:56320
	global_load_lds_dwordx4 v[6:7], off
	s_add_i32 m0, s25, 0x2000
	s_add_u32 s4, s4, 0x40080
	v_lshl_add_u64 v[6:7], v[234:235], 0, s[80:81]
	s_addc_u32 s5, s5, 0
	s_add_i32 s25, s63, s20
	global_load_lds_dwordx4 v[6:7], off
	v_lshl_add_u64 v[6:7], s[4:5], 0, v[134:135]
	s_mov_b32 m0, s25
	s_nop 0
	global_load_lds_dwordx4 v[6:7], off
	v_lshl_add_u64 v[6:7], s[4:5], 0, v[132:133]
	s_add_i32 m0, s25, 0x2000
	s_nop 0
	global_load_lds_dwordx4 v[6:7], off
	v_lshl_add_u64 v[6:7], v[236:237], 0, s[80:81]
	s_mov_b32 m0, s79
	s_nop 0
	global_load_lds_dwordx4 v[6:7], off
	v_lshl_add_u64 v[6:7], v[238:239], 0, s[80:81]
	s_mov_b32 m0, s82
	s_nop 0
	global_load_lds_dwordx4 v[6:7], off
	s_waitcnt vmcnt(8)
	s_waitcnt lgkmcnt(0)
	s_barrier
	s_waitcnt lgkmcnt(0)
	v_mfma_f32_16x16x32_bf16 v[64:67], v[146:149], v[202:205], v[64:67]
	v_mfma_f32_16x16x32_bf16 v[60:63], v[154:157], v[202:205], v[60:63]
	v_mfma_f32_16x16x32_bf16 v[56:59], v[146:149], v[210:213], v[56:59]
	v_mfma_f32_16x16x32_bf16 v[52:55], v[154:157], v[210:213], v[52:55]
	v_mfma_f32_16x16x32_bf16 v[48:51], v[146:149], v[218:221], v[48:51]
	v_mfma_f32_16x16x32_bf16 v[44:47], v[154:157], v[218:221], v[44:47]
	v_mfma_f32_16x16x32_bf16 v[40:43], v[146:149], v[226:229], v[40:43]
	v_mfma_f32_16x16x32_bf16 v[36:39], v[154:157], v[226:229], v[36:39]
	v_mfma_f32_16x16x32_bf16 v[64:67], v[150:153], v[206:209], v[64:67]
	v_mfma_f32_16x16x32_bf16 v[60:63], v[162:165], v[206:209], v[60:63]
	v_mfma_f32_16x16x32_bf16 v[56:59], v[150:153], v[214:217], v[56:59]
	v_mfma_f32_16x16x32_bf16 v[52:55], v[162:165], v[214:217], v[52:55]
	v_mfma_f32_16x16x32_bf16 v[48:51], v[150:153], v[222:225], v[48:51]
	v_mfma_f32_16x16x32_bf16 v[44:47], v[162:165], v[222:225], v[44:47]
	v_mfma_f32_16x16x32_bf16 v[40:43], v[150:153], v[230:233], v[40:43]
	v_mfma_f32_16x16x32_bf16 v[36:39], v[162:165], v[230:233], v[36:39]
	v_mfma_f32_16x16x32_bf16 v[32:35], v[166:169], v[202:205], v[32:35]
	v_mfma_f32_16x16x32_bf16 v[28:31], v[194:197], v[202:205], v[28:31]
	v_mfma_f32_16x16x32_bf16 v[24:27], v[166:169], v[210:213], v[24:27]
	v_mfma_f32_16x16x32_bf16 v[20:23], v[194:197], v[210:213], v[20:23]
	v_mfma_f32_16x16x32_bf16 v[16:19], v[166:169], v[218:221], v[16:19]
	v_mfma_f32_16x16x32_bf16 v[12:15], v[194:197], v[218:221], v[12:15]
	v_mfma_f32_16x16x32_bf16 v[6:9], v[166:169], v[226:229], v[8:11]
	v_mfma_f32_16x16x32_bf16 v[2:5], v[194:197], v[226:229], v[2:5]
	v_mfma_f32_16x16x32_bf16 v[32:35], v[190:193], v[206:209], v[32:35]
	v_mfma_f32_16x16x32_bf16 v[28:31], v[198:201], v[206:209], v[28:31]
	v_mfma_f32_16x16x32_bf16 v[24:27], v[190:193], v[214:217], v[24:27]
	v_mfma_f32_16x16x32_bf16 v[20:23], v[198:201], v[214:217], v[20:23]
	v_mfma_f32_16x16x32_bf16 v[16:19], v[190:193], v[222:225], v[16:19]
	v_mfma_f32_16x16x32_bf16 v[12:15], v[198:201], v[222:225], v[12:15]
	v_mfma_f32_16x16x32_bf16 v[8:11], v[190:193], v[230:233], v[6:9]
	v_mfma_f32_16x16x32_bf16 v[4:7], v[198:201], v[230:233], v[2:5]
	s_barrier
	s_add_u32 s10, s10, 0x100
	s_addc_u32 s11, s11, 0
	s_add_u32 s15, s15, 0x100
	s_addc_u32 s45, s45, 0
	s_cmp_ge_i32 s61, s74
	s_mov_b32 s4, s61
	s_cbranch_scc0 .LBB0_473
